# v17 + nt (non-temporal) hint on once-read f32 weight / x loads in conv+prep + final-norm loop rewritten: gains preloaded, 8 row loads issued together, counted vmcnt(7), nt output stores
# speedup vs baseline: 1.0070x; 1.0040x over previous
.LBB0_354:
	s_ashr_i32 s0, s4, 31
	s_lshr_b32 s0, s0, 27
	s_add_i32 s0, s4, s0
	s_ashr_i32 s1, s0, 5
	s_lshl_b32 s0, s1, 11
	s_lshl_b32 s2, s1, 6
	s_sub_i32 s0, s6, s0
	v_or_b32_e32 v2, s2, v66
	s_ashr_i32 s1, s0, 31
	v_ashrrev_i32_e32 v3, 31, v2
	v_lshl_add_u64 v[4:5], s[0:1], 2, v[62:63]
	v_lshlrev_b64 v[6:7], 13, v[2:3]
	v_lshl_add_u64 v[6:7], v[4:5], 0, v[6:7]
	global_load_dwordx4 v[70:73], v[6:7], off nt
	v_or_b32_e32 v6, 4, v2
	v_ashrrev_i32_e32 v7, 31, v6
	v_lshlrev_b64 v[6:7], 13, v[6:7]
	v_lshl_add_u64 v[6:7], v[4:5], 0, v[6:7]
	global_load_dwordx4 v[58:61], v[6:7], off nt
	v_or_b32_e32 v6, 8, v2
	v_ashrrev_i32_e32 v7, 31, v6
	v_lshlrev_b64 v[6:7], 13, v[6:7]
	v_lshl_add_u64 v[6:7], v[4:5], 0, v[6:7]
	global_load_dwordx4 v[54:57], v[6:7], off nt
	v_or_b32_e32 v6, 12, v2
	v_ashrrev_i32_e32 v7, 31, v6
	v_lshlrev_b64 v[6:7], 13, v[6:7]
	v_lshl_add_u64 v[6:7], v[4:5], 0, v[6:7]
	global_load_dwordx4 v[50:53], v[6:7], off nt
	v_or_b32_e32 v6, 16, v2
	v_ashrrev_i32_e32 v7, 31, v6
	v_lshlrev_b64 v[6:7], 13, v[6:7]
	v_lshl_add_u64 v[6:7], v[4:5], 0, v[6:7]
	global_load_dwordx4 v[46:49], v[6:7], off nt
	v_or_b32_e32 v6, 20, v2
	v_ashrrev_i32_e32 v7, 31, v6
	v_lshlrev_b64 v[6:7], 13, v[6:7]
	v_lshl_add_u64 v[6:7], v[4:5], 0, v[6:7]
	global_load_dwordx4 v[42:45], v[6:7], off nt
	v_or_b32_e32 v6, 24, v2
	v_ashrrev_i32_e32 v7, 31, v6
	v_lshlrev_b64 v[6:7], 13, v[6:7]
	v_lshl_add_u64 v[6:7], v[4:5], 0, v[6:7]
	global_load_dwordx4 v[38:41], v[6:7], off nt
	v_or_b32_e32 v6, 28, v2
	v_ashrrev_i32_e32 v7, 31, v6
	v_lshlrev_b64 v[6:7], 13, v[6:7]
	v_lshl_add_u64 v[6:7], v[4:5], 0, v[6:7]
	global_load_dwordx4 v[34:37], v[6:7], off nt
	v_or_b32_e32 v6, 32, v2
	v_ashrrev_i32_e32 v7, 31, v6
	v_lshlrev_b64 v[6:7], 13, v[6:7]
	v_lshl_add_u64 v[6:7], v[4:5], 0, v[6:7]
	global_load_dwordx4 v[30:33], v[6:7], off nt
	v_or_b32_e32 v6, 36, v2
	v_ashrrev_i32_e32 v7, 31, v6
	v_lshlrev_b64 v[6:7], 13, v[6:7]
	v_lshl_add_u64 v[6:7], v[4:5], 0, v[6:7]
	global_load_dwordx4 v[26:29], v[6:7], off nt
	v_or_b32_e32 v6, 40, v2
	v_ashrrev_i32_e32 v7, 31, v6
	v_lshlrev_b64 v[6:7], 13, v[6:7]
	v_lshl_add_u64 v[6:7], v[4:5], 0, v[6:7]
	global_load_dwordx4 v[22:25], v[6:7], off nt
	v_or_b32_e32 v6, 44, v2
	v_ashrrev_i32_e32 v7, 31, v6
	v_lshlrev_b64 v[6:7], 13, v[6:7]
	v_lshl_add_u64 v[6:7], v[4:5], 0, v[6:7]
	global_load_dwordx4 v[18:21], v[6:7], off nt
	v_or_b32_e32 v6, 48, v2
	v_ashrrev_i32_e32 v7, 31, v6
	v_lshlrev_b64 v[6:7], 13, v[6:7]
	v_lshl_add_u64 v[6:7], v[4:5], 0, v[6:7]
	global_load_dwordx4 v[14:17], v[6:7], off nt
	v_or_b32_e32 v6, 52, v2
	v_ashrrev_i32_e32 v7, 31, v6
	v_lshlrev_b64 v[6:7], 13, v[6:7]
	v_lshl_add_u64 v[6:7], v[4:5], 0, v[6:7]
	global_load_dwordx4 v[10:13], v[6:7], off nt
	v_or_b32_e32 v6, 56, v2
	v_ashrrev_i32_e32 v7, 31, v6
	v_lshlrev_b64 v[6:7], 13, v[6:7]
	v_or_b32_e32 v2, 60, v2
	v_lshl_add_u64 v[6:7], v[4:5], 0, v[6:7]
	v_ashrrev_i32_e32 v3, 31, v2
	global_load_dwordx4 v[6:9], v[6:7], off nt
	v_lshlrev_b64 v[2:3], 13, v[2:3]
	v_lshl_add_u64 v[2:3], v[4:5], 0, v[2:3]
	global_load_dwordx4 v[2:5], v[2:3], off nt
	v_add_u32_e32 v69, 0x410, v68
	s_waitcnt vmcnt(0)
	ds_write2_b32 v68, v70, v71 offset1:1
	ds_write2_b32 v68, v72, v73 offset0:2 offset1:3
	s_ashr_i32 s3, s2, 31
	s_add_i32 s4, s4, s5
	s_add_i32 s6, s6, s7
	s_cmpk_gt_i32 s4, 0xabf
	ds_write2_b32 v69, v58, v59 offset1:1
	v_add_u32_e32 v58, 0x418, v68
	ds_write2_b32 v58, v60, v61 offset1:1
	v_add_u32_e32 v58, 0x820, v68
	ds_write2_b32 v58, v54, v55 offset1:1
	v_add_u32_e32 v54, 0x828, v68
	ds_write2_b32 v54, v56, v57 offset1:1
	v_add_u32_e32 v54, 0xc30, v68
	ds_write2_b32 v54, v50, v51 offset1:1
	v_add_u32_e32 v50, 0xc38, v68
	ds_write2_b32 v50, v52, v53 offset1:1
	v_add_u32_e32 v50, 0x1040, v68
	ds_write2_b32 v50, v46, v47 offset1:1
	v_add_u32_e32 v46, 0x1048, v68
	ds_write2_b32 v46, v48, v49 offset1:1
	v_add_u32_e32 v46, 0x1450, v68
	ds_write2_b32 v46, v42, v43 offset1:1
	v_add_u32_e32 v42, 0x1458, v68
	ds_write2_b32 v42, v44, v45 offset1:1
	v_add_u32_e32 v42, 0x1860, v68
	ds_write2_b32 v42, v38, v39 offset1:1
	v_add_u32_e32 v38, 0x1868, v68
	ds_write2_b32 v38, v40, v41 offset1:1
	v_add_u32_e32 v38, 0x1c70, v68
	ds_write2_b32 v38, v34, v35 offset1:1
	v_add_u32_e32 v34, 0x1c78, v68
	ds_write2_b32 v34, v36, v37 offset1:1
	v_add_u32_e32 v34, 0x2080, v68
	ds_write2_b32 v34, v30, v31 offset1:1
	v_add_u32_e32 v30, 0x2088, v68
	ds_write2_b32 v30, v32, v33 offset1:1
	v_add_u32_e32 v30, 0x2490, v68
	ds_write2_b32 v30, v26, v27 offset1:1
	v_add_u32_e32 v26, 0x2498, v68
	ds_write2_b32 v26, v28, v29 offset1:1
	v_add_u32_e32 v26, 0x28a0, v68
	v_add_u32_e32 v27, s0, v1
	ds_write2_b32 v26, v22, v23 offset1:1
	v_add_u32_e32 v22, 0x28a8, v68
	ds_write2_b32 v22, v24, v25 offset1:1
	v_add_u32_e32 v22, 0x2cb0, v68
	v_add_u32_e32 v26, 0x400, v67
	ds_write2_b32 v22, v18, v19 offset1:1
	v_add_u32_e32 v18, 0x2cb8, v68
	ds_write2_b32 v18, v20, v21 offset1:1
	v_add_u32_e32 v18, 0x30c0, v68
	ds_write2_b32 v18, v14, v15 offset1:1
	v_add_u32_e32 v14, 0x30c8, v68
	ds_write2_b32 v14, v16, v17 offset1:1
	v_add_u32_e32 v14, 0x34d0, v68
	ds_write2_b32 v14, v10, v11 offset1:1
	v_add_u32_e32 v10, 0x34d8, v68
	ds_write2_b32 v10, v12, v13 offset1:1
	v_add_u32_e32 v10, 0x38e0, v68
	ds_write2_b32 v10, v6, v7 offset1:1
	v_add_u32_e32 v6, 0x38e8, v68
	ds_write2_b32 v6, v8, v9 offset1:1
	v_add_u32_e32 v6, 0x3cf0, v68
	ds_write2_b32 v6, v2, v3 offset1:1
	v_add_u32_e32 v2, 0x3cf8, v68
	ds_write2_b32 v2, v4, v5 offset1:1
	s_waitcnt lgkmcnt(0)
	ds_read2_b32 v[8:9], v67 offset0:65 offset1:73
	ds_read2_b32 v[10:11], v67 offset1:8
	ds_read2_b32 v[12:13], v67 offset0:130 offset1:138
	ds_read2_b32 v[14:15], v67 offset0:195 offset1:203
	ds_read2_b32 v[16:17], v26 offset0:4 offset1:12
	ds_read2_b32 v[18:19], v26 offset0:69 offset1:77
	ds_read2_b32 v[20:21], v26 offset0:134 offset1:142
	ds_read2_b32 v[22:23], v26 offset0:199 offset1:207
	v_lshl_add_u64 v[6:7], s[2:3], 1, v[64:65]
	s_waitcnt lgkmcnt(6)
	v_cvt_pk_bf16_f32 v2, v10, v8
	s_waitcnt lgkmcnt(4)
	v_cvt_pk_bf16_f32 v3, v12, v14
	s_waitcnt lgkmcnt(2)
	v_cvt_pk_bf16_f32 v4, v16, v18
	s_waitcnt lgkmcnt(0)
	v_cvt_pk_bf16_f32 v5, v20, v22
	v_mad_i64_i32 v[24:25], s[0:1], v27, s8, v[6:7]
	v_add_u32_e32 v8, 8, v27
	global_store_dwordx4 v[24:25], v[2:5], off
	s_nop 1
	v_cvt_pk_bf16_f32 v2, v11, v9
	v_cvt_pk_bf16_f32 v3, v13, v15
	v_cvt_pk_bf16_f32 v4, v17, v19
	v_cvt_pk_bf16_f32 v5, v21, v23
	v_mad_i64_i32 v[8:9], s[0:1], v8, s8, v[6:7]
	global_store_dwordx4 v[8:9], v[2:5], off
	ds_read2_b32 v[8:9], v67 offset0:81 offset1:89
	ds_read2_b32 v[10:11], v67 offset0:16 offset1:24
	ds_read2_b32 v[12:13], v67 offset0:146 offset1:154
	ds_read2_b32 v[14:15], v67 offset0:211 offset1:219
	ds_read2_b32 v[16:17], v26 offset0:20 offset1:28
	ds_read2_b32 v[18:19], v26 offset0:85 offset1:93
	ds_read2_b32 v[20:21], v26 offset0:150 offset1:158
	ds_read2_b32 v[22:23], v26 offset0:215 offset1:223
	s_waitcnt lgkmcnt(6)
	v_cvt_pk_bf16_f32 v2, v10, v8
	v_add_u32_e32 v8, 16, v27
	s_waitcnt lgkmcnt(4)
	v_cvt_pk_bf16_f32 v3, v12, v14
	s_waitcnt lgkmcnt(2)
	v_cvt_pk_bf16_f32 v4, v16, v18
	s_waitcnt lgkmcnt(0)
	v_cvt_pk_bf16_f32 v5, v20, v22
	v_mad_i64_i32 v[24:25], s[0:1], v8, s8, v[6:7]
	v_add_u32_e32 v8, 24, v27
	global_store_dwordx4 v[24:25], v[2:5], off
	s_nop 1
	v_cvt_pk_bf16_f32 v2, v11, v9
	v_cvt_pk_bf16_f32 v3, v13, v15
	v_cvt_pk_bf16_f32 v4, v17, v19
	v_cvt_pk_bf16_f32 v5, v21, v23
	v_mad_i64_i32 v[8:9], s[0:1], v8, s8, v[6:7]
	global_store_dwordx4 v[8:9], v[2:5], off
	ds_read2_b32 v[8:9], v67 offset0:32 offset1:40
	ds_read2_b32 v[10:11], v67 offset0:97 offset1:105
	ds_read2_b32 v[12:13], v67 offset0:162 offset1:170
	ds_read2_b32 v[14:15], v67 offset0:227 offset1:235
	ds_read2_b32 v[16:17], v26 offset0:36 offset1:44
	ds_read2_b32 v[18:19], v26 offset0:101 offset1:109
	ds_read2_b32 v[20:21], v26 offset0:166 offset1:174
	ds_read2_b32 v[22:23], v26 offset0:231 offset1:239
	s_waitcnt lgkmcnt(6)
	v_cvt_pk_bf16_f32 v2, v8, v10
	v_add_u32_e32 v8, 32, v27
	s_waitcnt lgkmcnt(4)
	v_cvt_pk_bf16_f32 v3, v12, v14
	s_waitcnt lgkmcnt(2)
	v_cvt_pk_bf16_f32 v4, v16, v18
	s_waitcnt lgkmcnt(0)
	v_cvt_pk_bf16_f32 v5, v20, v22
	v_mad_i64_i32 v[24:25], s[0:1], v8, s8, v[6:7]
	v_add_u32_e32 v8, 40, v27
	global_store_dwordx4 v[24:25], v[2:5], off
	s_nop 1
	v_cvt_pk_bf16_f32 v2, v9, v11
	v_cvt_pk_bf16_f32 v3, v13, v15
	v_cvt_pk_bf16_f32 v4, v17, v19
	v_cvt_pk_bf16_f32 v5, v21, v23
	v_mad_i64_i32 v[8:9], s[0:1], v8, s8, v[6:7]
	global_store_dwordx4 v[8:9], v[2:5], off
	ds_read2_b32 v[8:9], v67 offset0:48 offset1:56
	ds_read2_b32 v[10:11], v67 offset0:113 offset1:121
	ds_read2_b32 v[12:13], v67 offset0:178 offset1:186
	ds_read2_b32 v[14:15], v67 offset0:243 offset1:251
	ds_read2_b32 v[16:17], v26 offset0:52 offset1:60
	ds_read2_b32 v[18:19], v26 offset0:117 offset1:125
	ds_read2_b32 v[20:21], v26 offset0:182 offset1:190
	ds_read2_b32 v[22:23], v26 offset0:247 offset1:255
	s_waitcnt lgkmcnt(6)
	v_cvt_pk_bf16_f32 v2, v8, v10
	v_add_u32_e32 v8, 48, v27
	s_waitcnt lgkmcnt(4)
	v_cvt_pk_bf16_f32 v3, v12, v14
	s_waitcnt lgkmcnt(2)
	v_cvt_pk_bf16_f32 v4, v16, v18
	s_waitcnt lgkmcnt(0)
	v_cvt_pk_bf16_f32 v5, v20, v22
	v_mad_i64_i32 v[24:25], s[0:1], v8, s8, v[6:7]
	v_add_u32_e32 v8, 56, v27
	global_store_dwordx4 v[24:25], v[2:5], off
	v_mad_i64_i32 v[6:7], s[0:1], v8, s8, v[6:7]
	s_nop 0
	v_cvt_pk_bf16_f32 v2, v9, v11
	v_cvt_pk_bf16_f32 v3, v13, v15
	v_cvt_pk_bf16_f32 v4, v17, v19
	v_cvt_pk_bf16_f32 v5, v21, v23
	global_store_dwordx4 v[6:7], v[2:5], off
	s_waitcnt lgkmcnt(0)
	s_cbranch_scc0 .LBB0_354

.LBB0_361:
	global_load_dwordx4 v[6:9], v[38:39], off offset:-4096 nt
	global_load_dwordx4 v[2:5], v[38:39], off offset:-3072 nt
	global_load_dwordx4 v[10:13], v[38:39], off offset:-2048 nt
	global_load_dwordx4 v[14:17], v[38:39], off offset:-1024 nt
	global_load_dwordx4 v[18:21], v[38:39], off nt
	global_load_dwordx4 v[22:25], v[38:39], off offset:1024 nt
	global_load_dwordx4 v[26:29], v[38:39], off offset:2048 nt
	global_load_dwordx4 v[30:33], v[38:39], off offset:3072 nt
	s_waitcnt vmcnt(0)
	v_mul_f32_e32 v45, v7, v7
	s_waitcnt lgkmcnt(0)
	v_mul_f32_e32 v46, v9, v9
	v_mul_f32_e32 v47, v3, v3
	v_mul_f32_e32 v48, v5, v5
	v_mul_f32_e32 v49, v11, v11
	v_mul_f32_e32 v50, v13, v13
	v_fmac_f32_e32 v45, v6, v6
	v_fmac_f32_e32 v46, v8, v8
	v_fmac_f32_e32 v47, v2, v2
	v_fmac_f32_e32 v48, v4, v4
	v_mul_f32_e32 v51, v15, v15
	v_mul_f32_e32 v52, v17, v17
	v_fmac_f32_e32 v49, v10, v10
	v_fmac_f32_e32 v50, v12, v12
	v_add_f32_e32 v45, v45, v46
	v_add_f32_e32 v46, v47, v48
	v_mul_f32_e32 v53, v19, v19
	v_mul_f32_e32 v54, v21, v21
	v_fmac_f32_e32 v51, v14, v14
	v_fmac_f32_e32 v52, v16, v16
	v_add_f32_e32 v47, v49, v50
	v_add_f32_e32 v45, v45, v46
	v_mul_f32_e32 v55, v23, v23
	v_mul_f32_e32 v56, v25, v25
	v_fmac_f32_e32 v53, v18, v18
	v_fmac_f32_e32 v54, v20, v20
	v_add_f32_e32 v48, v51, v52
	v_add_f32_e32 v45, v45, v47
	v_mul_f32_e32 v57, v27, v27
	v_mul_f32_e32 v58, v29, v29
	v_fmac_f32_e32 v55, v22, v22
	v_fmac_f32_e32 v56, v24, v24
	v_add_f32_e32 v49, v53, v54
	v_add_f32_e32 v45, v45, v48
	v_mul_f32_e32 v59, v31, v31
	v_mul_f32_e32 v60, v33, v33
	v_fmac_f32_e32 v57, v26, v26
	v_fmac_f32_e32 v58, v28, v28
	v_add_f32_e32 v50, v55, v56
	v_add_f32_e32 v45, v45, v49
	v_fmac_f32_e32 v59, v30, v30
	v_fmac_f32_e32 v60, v32, v32
	v_add_f32_e32 v51, v57, v58
	v_add_f32_e32 v45, v45, v50
	v_add_f32_e32 v45, v45, v51
	v_add_f32_e32 v46, v59, v60
	v_add_f32_e32 v45, v45, v46
	ds_bpermute_b32 v46, v1, v45
	s_waitcnt lgkmcnt(0)
	v_add_f32_e32 v45, v45, v46
	ds_bpermute_b32 v46, v40, v45
	s_waitcnt lgkmcnt(0)
	v_add_f32_e32 v45, v45, v46
	ds_bpermute_b32 v46, v41, v45
	s_waitcnt lgkmcnt(0)
	v_add_f32_e32 v45, v45, v46
	ds_bpermute_b32 v46, v42, v45
	s_waitcnt lgkmcnt(0)
	v_add_f32_e32 v45, v45, v46
	ds_bpermute_b32 v46, v43, v45
	s_waitcnt lgkmcnt(0)
	v_add_f32_e32 v45, v45, v46
	ds_bpermute_b32 v46, v44, v45
	s_and_saveexec_b64 s[0:1], s[4:5]
	s_cbranch_execz .LBB0_360
	s_waitcnt lgkmcnt(0)
	v_add_f32_e32 v45, v45, v46
	v_cndmask_b32_e64 v45, 0, v45, s[6:7]
	v_lshl_add_u64 v[46:47], s[40:41], 0, v[34:35]
	global_store_dword v[46:47], v45, off
	s_branch .LBB0_360

.LBB0_364:
	s_and_b64 vcc, exec, s[0:1]
	s_cbranch_vccz .LBB0_371
	s_cmpk_gt_i32 s56, 0x3fff
	s_cbranch_scc1 .LBB0_370
	v_and_b32_e32 v1, 64, v220
	v_add_u32_e32 v2, 64, v1
	v_xor_b32_e32 v1, 1, v220
	v_cmp_lt_i32_e64 s[4:5], v1, v2
	s_waitcnt lgkmcnt(0)
	v_xor_b32_e32 v3, 2, v220
	v_lshlrev_b32_e32 v14, 4, v230
	v_cndmask_b32_e64 v1, v220, v1, s[4:5]
	v_cmp_lt_i32_e64 s[4:5], v3, v2
	v_mov_b32_e32 v15, v0
	s_mov_b64 s[0:1], 0x1000
	v_cndmask_b32_e64 v3, v220, v3, s[4:5]
	v_lshlrev_b32_e32 v18, 2, v3
	v_xor_b32_e32 v3, 4, v220
	v_cmp_lt_i32_e64 s[4:5], v3, v2
	s_ashr_i32 s57, s56, 31
	v_readlane_b32 s2, v250, 6
	v_cndmask_b32_e64 v3, v220, v3, s[4:5]
	v_lshlrev_b32_e32 v19, 2, v3
	v_xor_b32_e32 v3, 8, v220
	v_cmp_lt_i32_e64 s[4:5], v3, v2
	v_lshlrev_b32_e32 v12, 2, v230
	v_mov_b32_e32 v13, v0
	v_cndmask_b32_e64 v3, v220, v3, s[4:5]
	v_lshlrev_b32_e32 v20, 2, v3
	v_xor_b32_e32 v3, 16, v220
	v_cmp_lt_i32_e64 s[4:5], v3, v2
	v_lshlrev_b32_e32 v16, 3, v230
	v_mov_b32_e32 v17, v0
	v_cndmask_b32_e64 v3, v220, v3, s[4:5]
	v_lshlrev_b32_e32 v21, 2, v3
	v_xor_b32_e32 v3, 32, v220
	v_cmp_lt_i32_e64 s[4:5], v3, v2
	v_cmp_gt_u32_e32 vcc, 32, v230
	v_lshlrev_b32_e32 v1, 2, v1
	v_cndmask_b32_e64 v2, v220, v3, s[4:5]
	v_lshlrev_b32_e32 v22, 2, v2
	v_lshl_add_u64 v[2:3], s[36:37], 0, v[14:15]
	v_lshl_add_u64 v[4:5], v[2:3], 0, s[0:1]
	s_mov_b64 s[0:1], 0x1400
	v_lshl_add_u64 v[6:7], v[2:3], 0, s[0:1]
	s_mov_b64 s[0:1], 0x1800
	v_lshl_add_u64 v[8:9], v[2:3], 0, s[0:1]
	s_mov_b64 s[0:1], 0x1c00
	v_lshl_add_u64 v[10:11], v[2:3], 0, s[0:1]
	s_lshl_b64 s[0:1], s[56:57], 7
	s_add_u32 s0, s2, s0
	v_readlane_b32 s2, v250, 7
	s_addc_u32 s1, s2, s1
	v_lshl_add_u64 v[12:13], s[0:1], 0, v[12:13]
	s_lshl_b64 s[0:1], s[56:57], 13
	v_readlane_b32 s2, v251, 30
	s_add_u32 s0, s2, s0
	v_readlane_b32 s2, v251, 31
	s_addc_u32 s1, s2, s1
	v_lshl_add_u64 v[14:15], s[0:1], 0, v[14:15]
	s_lshl_b64 s[0:1], s[56:57], 12
	v_readlane_b32 s4, v250, 0
	v_readlane_b32 s5, v250, 1
	s_add_u32 s0, s4, s0
	s_addc_u32 s1, s5, s1
	v_lshl_add_u64 v[16:17], s[0:1], 0, v[16:17]
	s_mov_b32 s2, s56
	v_readlane_b32 s6, v250, 2
	v_readlane_b32 s7, v250, 3
	global_load_dwordx4 v[40:43], v[2:3], off
	global_load_dwordx4 v[44:47], v[2:3], off offset:1024
	global_load_dwordx4 v[48:51], v[2:3], off offset:2048
	global_load_dwordx4 v[52:55], v[2:3], off offset:3072
	global_load_dwordx4 v[56:59], v[4:5], off
	global_load_dwordx4 v[60:63], v[6:7], off
	global_load_dwordx4 v[64:67], v[8:9], off
	global_load_dwordx4 v[68:71], v[10:11], off
	s_branch .LBB0_368
.LBB0_367:
	s_or_b64 exec, exec, s[0:1]
	v_lshl_add_u64 v[28:29], s[40:41], 0, v[16:17]
	global_load_dwordx2 v[72:73], v[28:29], off nt
	global_load_dwordx2 v[74:75], v[28:29], off offset:512 nt
	global_load_dwordx2 v[76:77], v[28:29], off offset:1024 nt
	global_load_dwordx2 v[78:79], v[28:29], off offset:1536 nt
	global_load_dwordx2 v[80:81], v[28:29], off offset:2048 nt
	global_load_dwordx2 v[82:83], v[28:29], off offset:2560 nt
	global_load_dwordx2 v[84:85], v[28:29], off offset:3072 nt
	global_load_dwordx2 v[86:87], v[28:29], off offset:3584 nt
	s_waitcnt vmcnt(8)
	ds_bpermute_b32 v32, v1, v23
	v_lshl_add_u64 v[12:13], v[12:13], 0, s[26:27]
	v_lshl_add_u64 v[16:17], v[16:17], 0, s[38:39]
	s_waitcnt lgkmcnt(0)
	v_add_f32_e32 v23, v23, v32
	ds_bpermute_b32 v32, v18, v23
	s_waitcnt lgkmcnt(0)
	v_add_f32_e32 v23, v23, v32
	ds_bpermute_b32 v32, v19, v23
	s_waitcnt lgkmcnt(0)
	v_add_f32_e32 v23, v23, v32
	ds_bpermute_b32 v32, v20, v23
	s_waitcnt lgkmcnt(0)
	v_add_f32_e32 v23, v23, v32
	ds_bpermute_b32 v32, v21, v23
	s_waitcnt lgkmcnt(0)
	v_add_f32_e32 v23, v23, v32
	ds_bpermute_b32 v32, v22, v23
	s_waitcnt lgkmcnt(0)
	v_add_f32_e32 v23, v23, v32
	v_fmamk_f32 v23, v23, 0x3a000000, v216
	v_mul_f32_e32 v32, 0x4b800000, v23
	v_cmp_gt_f32_e64 s[4:5], s65, v23
	s_nop 1
	v_cndmask_b32_e64 v23, v23, v32, s[4:5]
	v_rsq_f32_e32 v23, v23
	s_nop 0
	v_mul_f32_e32 v32, 0x45800000, v23
	v_cndmask_b32_e64 v32, v23, v32, s[4:5]
	s_waitcnt vmcnt(7)
	v_lshlrev_b32_e32 v34, 16, v72
	v_and_b32_e32 v35, 0xffff0000, v72
	v_lshlrev_b32_e32 v30, 16, v73
	v_and_b32_e32 v31, 0xffff0000, v73
	v_pk_mul_f32 v[34:35], v[32:33], v[34:35] op_sel_hi:[0,1]
	v_pk_mul_f32 v[30:31], v[32:33], v[30:31] op_sel_hi:[0,1]
	v_pk_mul_f32 v[26:27], v[42:43], v[30:31]
	v_pk_mul_f32 v[24:25], v[40:41], v[34:35]
	global_store_dwordx4 v[14:15], v[24:27], off offset:-4096 nt
	s_waitcnt vmcnt(7)
	v_lshlrev_b32_e32 v34, 16, v74
	v_and_b32_e32 v35, 0xffff0000, v74
	v_lshlrev_b32_e32 v30, 16, v75
	v_and_b32_e32 v31, 0xffff0000, v75
	v_pk_mul_f32 v[34:35], v[32:33], v[34:35] op_sel_hi:[0,1]
	v_pk_mul_f32 v[30:31], v[32:33], v[30:31] op_sel_hi:[0,1]
	v_pk_mul_f32 v[26:27], v[46:47], v[30:31]
	v_pk_mul_f32 v[24:25], v[44:45], v[34:35]
	global_store_dwordx4 v[14:15], v[24:27], off offset:-3072 nt
	s_waitcnt vmcnt(7)
	v_lshlrev_b32_e32 v34, 16, v76
	v_and_b32_e32 v35, 0xffff0000, v76
	v_lshlrev_b32_e32 v30, 16, v77
	v_and_b32_e32 v31, 0xffff0000, v77
	v_pk_mul_f32 v[34:35], v[32:33], v[34:35] op_sel_hi:[0,1]
	v_pk_mul_f32 v[30:31], v[32:33], v[30:31] op_sel_hi:[0,1]
	v_pk_mul_f32 v[26:27], v[50:51], v[30:31]
	v_pk_mul_f32 v[24:25], v[48:49], v[34:35]
	global_store_dwordx4 v[14:15], v[24:27], off offset:-2048 nt
	s_waitcnt vmcnt(7)
	v_lshlrev_b32_e32 v34, 16, v78
	v_and_b32_e32 v35, 0xffff0000, v78
	v_lshlrev_b32_e32 v30, 16, v79
	v_and_b32_e32 v31, 0xffff0000, v79
	v_pk_mul_f32 v[34:35], v[32:33], v[34:35] op_sel_hi:[0,1]
	v_pk_mul_f32 v[30:31], v[32:33], v[30:31] op_sel_hi:[0,1]
	v_pk_mul_f32 v[26:27], v[54:55], v[30:31]
	v_pk_mul_f32 v[24:25], v[52:53], v[34:35]
	global_store_dwordx4 v[14:15], v[24:27], off offset:-1024 nt
	s_waitcnt vmcnt(7)
	v_lshlrev_b32_e32 v34, 16, v80
	v_and_b32_e32 v35, 0xffff0000, v80
	v_lshlrev_b32_e32 v30, 16, v81
	v_and_b32_e32 v31, 0xffff0000, v81
	v_pk_mul_f32 v[34:35], v[32:33], v[34:35] op_sel_hi:[0,1]
	v_pk_mul_f32 v[30:31], v[32:33], v[30:31] op_sel_hi:[0,1]
	v_pk_mul_f32 v[26:27], v[58:59], v[30:31]
	v_pk_mul_f32 v[24:25], v[56:57], v[34:35]
	global_store_dwordx4 v[14:15], v[24:27], off nt
	s_waitcnt vmcnt(7)
	v_lshlrev_b32_e32 v34, 16, v82
	v_and_b32_e32 v35, 0xffff0000, v82
	v_lshlrev_b32_e32 v30, 16, v83
	v_and_b32_e32 v31, 0xffff0000, v83
	v_pk_mul_f32 v[34:35], v[32:33], v[34:35] op_sel_hi:[0,1]
	v_pk_mul_f32 v[30:31], v[32:33], v[30:31] op_sel_hi:[0,1]
	v_pk_mul_f32 v[26:27], v[62:63], v[30:31]
	v_pk_mul_f32 v[24:25], v[60:61], v[34:35]
	global_store_dwordx4 v[14:15], v[24:27], off offset:1024 nt
	s_waitcnt vmcnt(7)
	v_lshlrev_b32_e32 v34, 16, v84
	v_and_b32_e32 v35, 0xffff0000, v84
	v_lshlrev_b32_e32 v30, 16, v85
	v_and_b32_e32 v31, 0xffff0000, v85
	v_pk_mul_f32 v[34:35], v[32:33], v[34:35] op_sel_hi:[0,1]
	v_pk_mul_f32 v[30:31], v[32:33], v[30:31] op_sel_hi:[0,1]
	v_pk_mul_f32 v[26:27], v[66:67], v[30:31]
	v_pk_mul_f32 v[24:25], v[64:65], v[34:35]
	global_store_dwordx4 v[14:15], v[24:27], off offset:2048 nt
	s_waitcnt vmcnt(7)
	v_lshlrev_b32_e32 v34, 16, v86
	v_and_b32_e32 v35, 0xffff0000, v86
	v_lshlrev_b32_e32 v30, 16, v87
	v_and_b32_e32 v31, 0xffff0000, v87
	v_pk_mul_f32 v[34:35], v[32:33], v[34:35] op_sel_hi:[0,1]
	v_pk_mul_f32 v[30:31], v[32:33], v[30:31] op_sel_hi:[0,1]
	v_pk_mul_f32 v[26:27], v[70:71], v[30:31]
	v_pk_mul_f32 v[24:25], v[68:69], v[34:35]
	global_store_dwordx4 v[14:15], v[24:27], off offset:3072 nt
	v_lshl_add_u64 v[14:15], v[14:15], 0, s[24:25]
	s_add_i32 s2, s2, s60
	s_cmpk_gt_i32 s2, 0x3fff
	s_cbranch_scc1 .LBB0_370

.LBB0_377:
	s_mul_hi_i32 s4, s18, 0x2fa0be83
	s_lshr_b32 s5, s4, 31
	s_ashr_i32 s19, s4, 5
	s_add_i32 s19, s19, s5
	s_mul_i32 s7, s19, 0xffffd500
	s_add_i32 s8, s16, s7
	s_lshl_b32 s6, s19, 6
	v_or_b32_e32 v78, s6, v1
	s_ashr_i32 s9, s8, 31
	v_lshl_add_u64 v[2:3], s[8:9], 2, v[74:75]
	v_or_b32_e32 v6, 4, v78
	v_mad_i64_i32 v[4:5], s[4:5], v78, s66, v[2:3]
	v_mad_i64_i32 v[6:7], s[4:5], v6, s66, v[2:3]
	global_load_dwordx4 v[62:65], v[4:5], off nt
	global_load_dwordx4 v[58:61], v[6:7], off nt
	v_or_b32_e32 v4, 8, v78
	v_or_b32_e32 v6, 12, v78
	v_mad_i64_i32 v[4:5], s[4:5], v4, s66, v[2:3]
	v_mad_i64_i32 v[6:7], s[4:5], v6, s66, v[2:3]
	global_load_dwordx4 v[54:57], v[4:5], off nt
	global_load_dwordx4 v[50:53], v[6:7], off nt
	v_or_b32_e32 v4, 16, v78
	v_or_b32_e32 v6, 20, v78
	v_mad_i64_i32 v[4:5], s[4:5], v4, s66, v[2:3]
	v_mad_i64_i32 v[6:7], s[4:5], v6, s66, v[2:3]
	global_load_dwordx4 v[46:49], v[4:5], off nt
	global_load_dwordx4 v[42:45], v[6:7], off nt
	v_or_b32_e32 v4, 24, v78
	v_or_b32_e32 v6, 28, v78
	v_mad_i64_i32 v[4:5], s[4:5], v4, s66, v[2:3]
	v_mad_i64_i32 v[6:7], s[4:5], v6, s66, v[2:3]
	global_load_dwordx4 v[38:41], v[4:5], off nt
	global_load_dwordx4 v[34:37], v[6:7], off nt
	v_or_b32_e32 v4, 32, v78
	v_or_b32_e32 v6, 36, v78
	v_mad_i64_i32 v[4:5], s[4:5], v4, s66, v[2:3]
	v_mad_i64_i32 v[6:7], s[4:5], v6, s66, v[2:3]
	global_load_dwordx4 v[30:33], v[4:5], off nt
	global_load_dwordx4 v[26:29], v[6:7], off nt
	v_or_b32_e32 v4, 40, v78
	v_or_b32_e32 v6, 44, v78
	v_mad_i64_i32 v[4:5], s[4:5], v4, s66, v[2:3]
	v_mad_i64_i32 v[6:7], s[4:5], v6, s66, v[2:3]
	global_load_dwordx4 v[22:25], v[4:5], off nt
	global_load_dwordx4 v[18:21], v[6:7], off nt
	v_or_b32_e32 v4, 48, v78
	v_or_b32_e32 v6, 52, v78
	v_mad_i64_i32 v[4:5], s[4:5], v4, s66, v[2:3]
	v_mad_i64_i32 v[6:7], s[4:5], v6, s66, v[2:3]
	global_load_dwordx4 v[14:17], v[4:5], off nt
	global_load_dwordx4 v[10:13], v[6:7], off nt
	v_or_b32_e32 v4, 56, v78
	v_or_b32_e32 v6, 60, v78
	v_mad_i64_i32 v[4:5], s[4:5], v4, s66, v[2:3]
	v_mad_i64_i32 v[2:3], s[4:5], v6, s66, v[2:3]
	global_load_dwordx4 v[6:9], v[4:5], off nt
	s_nop 0
	global_load_dwordx4 v[2:5], v[2:3], off nt
	v_ashrrev_i32_e32 v79, 31, v78
	v_cndmask_b32_e64 v67, 0, 1, s[80:81]
	v_cmp_ne_u32_e64 s[4:5], 1, v67
	s_andn2_b64 vcc, exec, s[80:81]
	v_lshl_add_u64 v[78:79], v[78:79], 2, s[2:3]
	s_cbranch_vccnz .LBB0_400
	global_load_dword v88, v[78:79], off
	global_load_dword v80, v[78:79], off offset:16
	s_waitcnt vmcnt(0)
	v_pk_mul_f32 v[90:91], v[62:63], v[88:89] op_sel_hi:[1,0]
	v_pk_mul_f32 v[88:89], v[64:65], v[88:89] op_sel_hi:[1,0]
	ds_write2_b32 v99, v90, v91 offset1:1
	ds_write2_b32 v99, v88, v89 offset0:2 offset1:3
	s_cbranch_execnz .LBB0_380

.LBB0_411:
	s_mul_hi_i32 s0, s5, 0x38e38e39
	s_lshr_b32 s1, s0, 31
	s_ashr_i32 s0, s0, 6
	s_add_i32 s1, s0, s1
	s_lshl_b32 s0, s1, 6
	v_or_b32_e32 v14, s0, v1
	v_ashrrev_i32_e32 v15, 31, v14
	v_lshl_add_u64 v[30:31], v[14:15], 2, s[82:83]
	global_load_dword v30, v[30:31], off
	s_mul_i32 s2, s1, 0xffffb800
	s_add_i32 s2, s4, s2
	s_ashr_i32 s3, s2, 31
	v_or_b32_e32 v10, 12, v14
	v_or_b32_e32 v12, 16, v14
	v_or_b32_e32 v16, 20, v14
	v_or_b32_e32 v18, 24, v14
	v_or_b32_e32 v20, 28, v14
	v_or_b32_e32 v6, 4, v14
	v_or_b32_e32 v8, 8, v14
	v_lshl_add_u64 v[76:77], s[2:3], 2, v[2:3]
	v_ashrrev_i32_e32 v11, 31, v10
	v_ashrrev_i32_e32 v13, 31, v12
	v_ashrrev_i32_e32 v17, 31, v16
	v_ashrrev_i32_e32 v19, 31, v18
	v_ashrrev_i32_e32 v21, 31, v20
	v_ashrrev_i32_e32 v7, 31, v6
	v_ashrrev_i32_e32 v9, 31, v8
	v_mad_i64_i32 v[32:33], s[6:7], v14, s61, v[76:77]
	v_mad_i64_i32 v[34:35], s[6:7], v6, s61, v[76:77]
	v_mad_i64_i32 v[42:43], s[6:7], v16, s61, v[76:77]
	v_mad_i64_i32 v[44:45], s[6:7], v18, s61, v[76:77]
	v_mad_i64_i32 v[78:79], s[6:7], v20, s61, v[76:77]
	v_lshl_add_u64 v[50:51], v[10:11], 2, s[82:83]
	v_lshl_add_u64 v[52:53], v[12:13], 2, s[82:83]
	v_lshl_add_u64 v[16:17], v[16:17], 2, s[82:83]
	v_lshl_add_u64 v[18:19], v[18:19], 2, s[82:83]
	v_lshl_add_u64 v[20:21], v[20:21], 2, s[82:83]
	v_mad_i64_i32 v[36:37], s[6:7], v8, s61, v[76:77]
	v_mad_i64_i32 v[38:39], s[6:7], v10, s61, v[76:77]
	v_mad_i64_i32 v[40:41], s[6:7], v12, s61, v[76:77]
	v_lshl_add_u64 v[46:47], v[6:7], 2, s[82:83]
	v_lshl_add_u64 v[48:49], v[8:9], 2, s[82:83]
	global_load_dwordx4 v[6:9], v[32:33], off nt
	global_load_dwordx4 v[10:13], v[34:35], off nt
	s_nop 0
	global_load_dword v32, v[46:47], off
	global_load_dword v34, v[48:49], off
	s_nop 0
	global_load_dword v50, v[50:51], off
	s_nop 0
	global_load_dword v52, v[52:53], off
	s_nop 0
	global_load_dword v16, v[16:17], off
	s_nop 0
	global_load_dword v18, v[18:19], off
	s_nop 0
	global_load_dword v20, v[20:21], off
	v_or_b32_e32 v22, 32, v14
	v_or_b32_e32 v24, 36, v14
	v_or_b32_e32 v26, 40, v14
	v_ashrrev_i32_e32 v23, 31, v22
	v_or_b32_e32 v28, 44, v14
	v_ashrrev_i32_e32 v25, 31, v24
	v_ashrrev_i32_e32 v27, 31, v26
	v_or_b32_e32 v74, 48, v14
	v_or_b32_e32 v88, 60, v14
	v_ashrrev_i32_e32 v29, 31, v28
	v_ashrrev_i32_e32 v75, 31, v74
	v_ashrrev_i32_e32 v89, 31, v88
	v_add_u32_e32 v67, 0x410, v99
	s_mulk_i32 s1, 0xfee0
	s_add_i32 s3, s5, s1
	s_ashr_i32 s1, s0, 31
	s_ashr_i32 s3, s3, 5
	s_and_b32 s2, s2, 0x7c0
	s_add_i32 s5, s5, s60
	s_add_i32 s4, s4, s33
	s_waitcnt vmcnt(0)
	v_pk_mul_f32 v[48:49], v[6:7], v[30:31] op_sel_hi:[1,0]
	v_pk_mul_f32 v[46:47], v[8:9], v[30:31] op_sel_hi:[1,0]
	global_load_dwordx4 v[6:9], v[36:37], off nt
	v_pk_mul_f32 v[72:73], v[10:11], v[32:33] op_sel_hi:[1,0]
	v_pk_mul_f32 v[70:71], v[12:13], v[32:33] op_sel_hi:[1,0]
	global_load_dwordx4 v[10:13], v[38:39], off nt
	s_waitcnt vmcnt(1)
	v_pk_mul_f32 v[64:65], v[6:7], v[34:35] op_sel_hi:[1,0]
	v_pk_mul_f32 v[62:63], v[8:9], v[34:35] op_sel_hi:[1,0]
	global_load_dwordx4 v[6:9], v[40:41], off nt
	s_waitcnt vmcnt(1)
	v_pk_mul_f32 v[60:61], v[10:11], v[50:51] op_sel_hi:[1,0]
	v_pk_mul_f32 v[58:59], v[12:13], v[50:51] op_sel_hi:[1,0]
	global_load_dwordx4 v[10:13], v[42:43], off nt
	s_waitcnt vmcnt(1)
	v_pk_mul_f32 v[56:57], v[6:7], v[52:53] op_sel_hi:[1,0]
	v_pk_mul_f32 v[54:55], v[8:9], v[52:53] op_sel_hi:[1,0]
	global_load_dwordx4 v[6:9], v[44:45], off nt
	s_waitcnt vmcnt(1)
	v_pk_mul_f32 v[52:53], v[10:11], v[16:17] op_sel_hi:[1,0]
	v_pk_mul_f32 v[50:51], v[12:13], v[16:17] op_sel_hi:[1,0]
	global_load_dwordx4 v[10:13], v[78:79], off nt
	v_or_b32_e32 v16, 52, v14
	v_or_b32_e32 v78, 56, v14
	v_ashrrev_i32_e32 v17, 31, v16
	v_ashrrev_i32_e32 v79, 31, v78
	s_waitcnt vmcnt(1)
	v_pk_mul_f32 v[34:35], v[8:9], v[18:19] op_sel_hi:[1,0]
	v_lshl_add_u64 v[8:9], v[22:23], 2, s[82:83]
	v_pk_mul_f32 v[40:41], v[6:7], v[18:19] op_sel_hi:[1,0]
	s_waitcnt vmcnt(0)
	v_pk_mul_f32 v[30:31], v[12:13], v[20:21] op_sel_hi:[1,0]
	v_lshl_add_u64 v[12:13], v[24:25], 2, s[82:83]
	global_load_dword v14, v[8:9], off
	global_load_dword v18, v[12:13], off
	v_lshl_add_u64 v[8:9], v[26:27], 2, s[82:83]
	v_pk_mul_f32 v[32:33], v[10:11], v[20:21] op_sel_hi:[1,0]
	global_load_dword v20, v[8:9], off
	v_lshl_add_u64 v[8:9], v[28:29], 2, s[82:83]
	v_mad_i64_i32 v[6:7], s[6:7], v22, s61, v[76:77]
	global_load_dword v22, v[8:9], off
	v_lshl_add_u64 v[8:9], v[74:75], 2, s[82:83]
	v_mad_i64_i32 v[10:11], s[6:7], v24, s61, v[76:77]
	global_load_dword v24, v[8:9], off
	v_lshl_add_u64 v[8:9], v[16:17], 2, s[82:83]
	global_load_dword v80, v[8:9], off
	v_lshl_add_u64 v[8:9], v[78:79], 2, s[82:83]
	global_load_dword v90, v[8:9], off
	v_lshl_add_u64 v[8:9], v[88:89], 2, s[82:83]
	global_load_dword v92, v[8:9], off
	s_nop 0
	global_load_dwordx4 v[6:9], v[6:7], off nt
	s_nop 0
	global_load_dwordx4 v[10:13], v[10:11], off nt
	s_waitcnt vmcnt(1)
	v_pk_mul_f32 v[44:45], v[6:7], v[14:15] op_sel_hi:[1,0]
	s_waitcnt vmcnt(0)
	v_pk_mul_f32 v[38:39], v[10:11], v[18:19] op_sel_hi:[1,0]
	v_mad_i64_i32 v[6:7], s[6:7], v26, s61, v[76:77]
	v_mad_i64_i32 v[10:11], s[6:7], v28, s61, v[76:77]
	v_pk_mul_f32 v[42:43], v[8:9], v[14:15] op_sel_hi:[1,0]
	v_pk_mul_f32 v[36:37], v[12:13], v[18:19] op_sel_hi:[1,0]
	global_load_dwordx4 v[6:9], v[6:7], off nt
	s_nop 0
	global_load_dwordx4 v[10:13], v[10:11], off nt
	v_mad_i64_i32 v[14:15], s[6:7], v74, s61, v[76:77]
	v_mad_i64_i32 v[18:19], s[6:7], v16, s61, v[76:77]
	v_mad_i64_i32 v[26:27], s[6:7], v88, s61, v[76:77]
	s_waitcnt vmcnt(1)
	v_pk_mul_f32 v[6:7], v[6:7], v[20:21] op_sel_hi:[1,0]
	v_pk_mul_f32 v[8:9], v[8:9], v[20:21] op_sel_hi:[1,0]
	global_load_dwordx4 v[14:17], v[14:15], off nt
	s_nop 0
	global_load_dwordx4 v[18:21], v[18:19], off nt
	s_waitcnt vmcnt(2)
	v_pk_mul_f32 v[10:11], v[10:11], v[22:23] op_sel_hi:[1,0]
	v_pk_mul_f32 v[12:13], v[12:13], v[22:23] op_sel_hi:[1,0]
	v_mad_i64_i32 v[22:23], s[6:7], v78, s61, v[76:77]
	s_waitcnt vmcnt(1)
	v_pk_mul_f32 v[14:15], v[14:15], v[24:25] op_sel_hi:[1,0]
	v_pk_mul_f32 v[16:17], v[16:17], v[24:25] op_sel_hi:[1,0]
	global_load_dwordx4 v[22:25], v[22:23], off nt
	s_nop 0
	global_load_dwordx4 v[26:29], v[26:27], off nt
	ds_write2_b32 v67, v72, v73 offset1:1
	v_add_u32_e32 v67, 0x418, v99
	ds_write2_b32 v67, v70, v71 offset1:1
	v_add_u32_e32 v67, 0x820, v99
	ds_write2_b32 v67, v64, v65 offset1:1
	v_add_u32_e32 v64, 0x828, v99
	ds_write2_b32 v64, v62, v63 offset1:1
	v_add_u32_e32 v62, 0xc30, v99
	ds_write2_b32 v62, v60, v61 offset1:1
	v_add_u32_e32 v60, 0xc38, v99
	ds_write2_b32 v60, v58, v59 offset1:1
	v_add_u32_e32 v58, 0x1040, v99
	ds_write2_b32 v58, v56, v57 offset1:1
	v_add_u32_e32 v58, 0x1458, v99
	v_add_u32_e32 v59, 0x1c70, v99
	ds_write2_b32 v58, v50, v51 offset1:1
	ds_write2_b32 v59, v32, v33 offset1:1
	v_lshl_add_u64 v[58:59], s[0:1], 1, v[4:5]
	s_mul_hi_i32 s0, s3, 0x55555556
	s_lshr_b32 s1, s0, 31
	s_add_i32 s0, s0, s1
	s_mul_i32 s1, s0, -3
	s_add_i32 s1, s1, s3
	s_lshl_b32 s0, s0, 11
	s_mulk_i32 s1, 0x1800
	v_add_u32_e32 v56, 0x1048, v99
	v_add_u32_e32 v57, 0x1450, v99
	s_add_i32 s1, s1, s0
	ds_write2_b32 v56, v54, v55 offset1:1
	v_add_u32_e32 v54, 0x1860, v99
	v_add_u32_e32 v55, 0x1868, v99
	ds_write2_b32 v57, v52, v53 offset1:1
	v_add_u32_e32 v57, 0x1c78, v99
	v_add_u32_e32 v60, 0x2080, v99
	v_add_u32_e32 v61, 0x2088, v99
	v_add_u32_e32 v62, 0x2490, v99
	v_add_u32_e32 v63, 0x2498, v99
	s_or_b32 s0, s1, s2
	ds_write2_b32 v54, v40, v41 offset1:1
	ds_write2_b32 v55, v34, v35 offset1:1
	ds_write2_b32 v57, v30, v31 offset1:1
	v_or_b32_e32 v30, s0, v100
	v_or_b32_e32 v32, s0, v81
	ds_write2_b32 v60, v44, v45 offset1:1
	v_or_b32_e32 v34, s0, v82
	ds_write2_b32 v61, v42, v43 offset1:1
	v_or_b32_e32 v40, s0, v83
	v_or_b32_e32 v42, s0, v84
	ds_write2_b32 v62, v38, v39 offset1:1
	v_or_b32_e32 v38, s0, v85
	ds_write2_b32 v63, v36, v37 offset1:1
	v_or_b32_e32 v36, s0, v86
	v_or_b32_e32 v44, s0, v87
	v_ashrrev_i32_e32 v31, 31, v30
	v_ashrrev_i32_e32 v33, 31, v32
	v_ashrrev_i32_e32 v35, 31, v34
	v_ashrrev_i32_e32 v41, 31, v40
	v_ashrrev_i32_e32 v43, 31, v42
	v_ashrrev_i32_e32 v39, 31, v38
	v_ashrrev_i32_e32 v37, 31, v36
	v_ashrrev_i32_e32 v45, 31, v44
	v_add_u32_e32 v50, 0x28a0, v99
	v_lshlrev_b64 v[30:31], 12, v[30:31]
	v_lshlrev_b64 v[32:33], 12, v[32:33]
	v_lshlrev_b64 v[34:35], 12, v[34:35]
	v_lshlrev_b64 v[40:41], 12, v[40:41]
	v_lshlrev_b64 v[42:43], 12, v[42:43]
	v_lshlrev_b64 v[60:61], 12, v[38:39]
	v_lshlrev_b64 v[62:63], 12, v[36:37]
	v_lshlrev_b64 v[44:45], 12, v[44:45]
	s_waitcnt vmcnt(2)
	v_pk_mul_f32 v[18:19], v[18:19], v[80:81] op_sel_hi:[1,0]
	v_pk_mul_f32 v[20:21], v[20:21], v[80:81] op_sel_hi:[1,0]
	v_add_u32_e32 v51, 0x28a8, v99
	v_add_u32_e32 v52, 0x2cb0, v99
	v_add_u32_e32 v53, 0x2cb8, v99
	v_add_u32_e32 v54, 0x30c0, v99
	v_add_u32_e32 v55, 0x30c8, v99
	v_add_u32_e32 v56, 0x34d0, v99
	s_waitcnt vmcnt(1)
	v_pk_mul_f32 v[22:23], v[22:23], v[90:91] op_sel_hi:[1,0]
	v_pk_mul_f32 v[24:25], v[24:25], v[90:91] op_sel_hi:[1,0]
	s_waitcnt vmcnt(0)
	v_pk_mul_f32 v[26:27], v[26:27], v[92:93] op_sel_hi:[1,0]
	v_pk_mul_f32 v[28:29], v[28:29], v[92:93] op_sel_hi:[1,0]
	v_lshl_add_u64 v[30:31], v[58:59], 0, v[30:31]
	v_lshl_add_u64 v[32:33], v[58:59], 0, v[32:33]
	v_lshl_add_u64 v[34:35], v[58:59], 0, v[34:35]
	v_lshl_add_u64 v[36:37], v[58:59], 0, v[40:41]
	v_lshl_add_u64 v[38:39], v[58:59], 0, v[42:43]
	v_lshl_add_u64 v[40:41], v[58:59], 0, v[60:61]
	v_lshl_add_u64 v[42:43], v[58:59], 0, v[62:63]
	v_lshl_add_u64 v[44:45], v[58:59], 0, v[44:45]
	v_add_u32_e32 v57, 0x34d8, v99
	v_add_u32_e32 v58, 0x38e0, v99
	ds_write2_b32 v99, v48, v49 offset1:1
	v_add_u32_e32 v48, 0x38e8, v99
	v_add_u32_e32 v49, 0x3cf0, v99
	ds_write2_b32 v99, v46, v47 offset0:2 offset1:3
	v_add_u32_e32 v47, 0x3cf8, v99
	ds_write2_b32 v50, v6, v7 offset1:1
	ds_write2_b32 v51, v8, v9 offset1:1
	ds_write2_b32 v52, v10, v11 offset1:1
	ds_write2_b32 v53, v12, v13 offset1:1
	ds_write2_b32 v54, v14, v15 offset1:1
	ds_write2_b32 v55, v16, v17 offset1:1
	ds_write2_b32 v56, v18, v19 offset1:1
	ds_write2_b32 v57, v20, v21 offset1:1
	ds_write2_b32 v58, v22, v23 offset1:1
	ds_write2_b32 v48, v24, v25 offset1:1
	ds_write2_b32 v49, v26, v27 offset1:1
	ds_write2_b32 v47, v28, v29 offset1:1
	s_waitcnt lgkmcnt(0)
	v_add_u32_e32 v46, 0x400, v101
	ds_read2_b32 v[8:9], v101 offset0:65 offset1:73
	ds_read2_b32 v[10:11], v101 offset1:8
	ds_read2_b32 v[12:13], v101 offset0:130 offset1:138
	ds_read2_b32 v[14:15], v101 offset0:195 offset1:203
	ds_read2_b32 v[16:17], v46 offset0:4 offset1:12
	ds_read2_b32 v[18:19], v46 offset0:69 offset1:77
	ds_read2_b32 v[20:21], v46 offset0:134 offset1:142
	ds_read2_b32 v[22:23], v46 offset0:199 offset1:207
	ds_read2_b32 v[24:25], v101 offset0:81 offset1:89
	ds_read2_b32 v[26:27], v101 offset0:16 offset1:24
	ds_read2_b32 v[28:29], v101 offset0:146 offset1:154
	ds_read2_b32 v[48:49], v101 offset0:211 offset1:219
	ds_read2_b32 v[50:51], v46 offset0:20 offset1:28
	ds_read2_b32 v[52:53], v46 offset0:85 offset1:93
	ds_read2_b32 v[54:55], v46 offset0:150 offset1:158
	ds_read2_b32 v[56:57], v46 offset0:215 offset1:223
	ds_read2_b32 v[58:59], v101 offset0:32 offset1:40
	ds_read2_b32 v[60:61], v101 offset0:97 offset1:105
	s_waitcnt lgkmcnt(14)
	v_cvt_pk_bf16_f32 v6, v10, v8
	v_cvt_pk_bf16_f32 v7, v12, v14
	v_cvt_pk_bf16_f32 v10, v11, v9
	v_cvt_pk_bf16_f32 v11, v13, v15
	s_waitcnt lgkmcnt(12)
	v_cvt_pk_bf16_f32 v8, v16, v18
	v_cvt_pk_bf16_f32 v12, v17, v19
	ds_read2_b32 v[62:63], v101 offset0:162 offset1:170
	ds_read2_b32 v[64:65], v101 offset0:227 offset1:235
	s_waitcnt lgkmcnt(12)
	v_cvt_pk_bf16_f32 v9, v20, v22
	v_cvt_pk_bf16_f32 v13, v21, v23
	s_waitcnt lgkmcnt(10)
	v_cvt_pk_bf16_f32 v14, v26, v24
	s_waitcnt lgkmcnt(8)
	v_cvt_pk_bf16_f32 v15, v28, v48
	v_cvt_pk_bf16_f32 v18, v27, v25
	v_cvt_pk_bf16_f32 v19, v29, v49
	ds_read2_b32 v[24:25], v46 offset0:36 offset1:44
	ds_read2_b32 v[28:29], v46 offset0:101 offset1:109
	s_waitcnt lgkmcnt(8)
	v_cvt_pk_bf16_f32 v16, v50, v52
	v_cvt_pk_bf16_f32 v20, v51, v53
	ds_read2_b32 v[48:49], v46 offset0:166 offset1:174
	ds_read2_b32 v[50:51], v46 offset0:231 offset1:239
	s_waitcnt lgkmcnt(8)
	v_cvt_pk_bf16_f32 v17, v54, v56
	v_cvt_pk_bf16_f32 v21, v55, v57
	s_waitcnt lgkmcnt(6)
	v_cvt_pk_bf16_f32 v22, v58, v60
	v_cvt_pk_bf16_f32 v26, v59, v61
	ds_read2_b32 v[52:53], v101 offset0:48 offset1:56
	ds_read2_b32 v[54:55], v101 offset0:113 offset1:121
	ds_read2_b32 v[56:57], v101 offset0:178 offset1:186
	ds_read2_b32 v[58:59], v101 offset0:243 offset1:251
	s_waitcnt lgkmcnt(6)
	v_cvt_pk_bf16_f32 v24, v24, v28
	v_cvt_pk_bf16_f32 v28, v25, v29
	s_waitcnt lgkmcnt(4)
	v_cvt_pk_bf16_f32 v25, v48, v50
	v_cvt_pk_bf16_f32 v29, v49, v51
	s_waitcnt lgkmcnt(2)
	v_cvt_pk_bf16_f32 v48, v52, v54
	s_waitcnt lgkmcnt(0)
	v_cvt_pk_bf16_f32 v49, v56, v58
	v_cvt_pk_bf16_f32 v52, v53, v55
	v_cvt_pk_bf16_f32 v53, v57, v59
	ds_read2_b32 v[50:51], v46 offset0:52 offset1:60
	ds_read2_b32 v[54:55], v46 offset0:117 offset1:125
	ds_read2_b32 v[56:57], v46 offset0:182 offset1:190
	ds_read2_b32 v[46:47], v46 offset0:247 offset1:255
	v_cvt_pk_bf16_f32 v23, v62, v64
	v_cvt_pk_bf16_f32 v27, v63, v65
	s_cmpk_lt_i32 s5, 0x2400
	s_waitcnt lgkmcnt(2)
	v_cvt_pk_bf16_f32 v50, v50, v54
	v_cvt_pk_bf16_f32 v54, v51, v55
	s_waitcnt lgkmcnt(0)
	v_cvt_pk_bf16_f32 v51, v56, v46
	v_cvt_pk_bf16_f32 v55, v57, v47
	global_store_dwordx4 v[30:31], v[6:9], off
	global_store_dwordx4 v[32:33], v[10:13], off
	global_store_dwordx4 v[34:35], v[14:17], off
	global_store_dwordx4 v[36:37], v[18:21], off
	global_store_dwordx4 v[38:39], v[22:25], off
	global_store_dwordx4 v[40:41], v[26:29], off
	global_store_dwordx4 v[42:43], v[48:51], off
	global_store_dwordx4 v[44:45], v[52:55], off
	s_waitcnt lgkmcnt(0)
	s_cbranch_scc1 .LBB0_411

.LBB0_414:
	s_ashr_i32 s2, s7, 31
	s_lshr_b32 s2, s2, 27
	s_add_i32 s2, s7, s2
	s_ashr_i32 s3, s2, 5
	s_lshl_b32 s2, s3, 11
	s_lshl_b32 s4, s3, 6
	s_sub_i32 s2, s6, s2
	v_or_b32_e32 v2, s4, v1
	s_ashr_i32 s3, s2, 31
	v_ashrrev_i32_e32 v3, 31, v2
	v_lshl_add_u64 v[4:5], s[2:3], 2, v[62:63]
	v_lshlrev_b64 v[6:7], 13, v[2:3]
	v_lshl_add_u64 v[6:7], v[4:5], 0, v[6:7]
	global_load_dwordx4 v[70:73], v[6:7], off nt
	v_or_b32_e32 v6, 4, v2
	v_ashrrev_i32_e32 v7, 31, v6
	v_lshlrev_b64 v[6:7], 13, v[6:7]
	v_lshl_add_u64 v[6:7], v[4:5], 0, v[6:7]
	global_load_dwordx4 v[58:61], v[6:7], off nt
	v_or_b32_e32 v6, 8, v2
	v_ashrrev_i32_e32 v7, 31, v6
	v_lshlrev_b64 v[6:7], 13, v[6:7]
	v_lshl_add_u64 v[6:7], v[4:5], 0, v[6:7]
	global_load_dwordx4 v[54:57], v[6:7], off nt
	v_or_b32_e32 v6, 12, v2
	v_ashrrev_i32_e32 v7, 31, v6
	v_lshlrev_b64 v[6:7], 13, v[6:7]
	v_lshl_add_u64 v[6:7], v[4:5], 0, v[6:7]
	global_load_dwordx4 v[50:53], v[6:7], off nt
	v_or_b32_e32 v6, 16, v2
	v_ashrrev_i32_e32 v7, 31, v6
	v_lshlrev_b64 v[6:7], 13, v[6:7]
	v_lshl_add_u64 v[6:7], v[4:5], 0, v[6:7]
	global_load_dwordx4 v[46:49], v[6:7], off nt
	v_or_b32_e32 v6, 20, v2
	v_ashrrev_i32_e32 v7, 31, v6
	v_lshlrev_b64 v[6:7], 13, v[6:7]
	v_lshl_add_u64 v[6:7], v[4:5], 0, v[6:7]
	global_load_dwordx4 v[42:45], v[6:7], off nt
	v_or_b32_e32 v6, 24, v2
	v_ashrrev_i32_e32 v7, 31, v6
	v_lshlrev_b64 v[6:7], 13, v[6:7]
	v_lshl_add_u64 v[6:7], v[4:5], 0, v[6:7]
	global_load_dwordx4 v[38:41], v[6:7], off nt
	v_or_b32_e32 v6, 28, v2
	v_ashrrev_i32_e32 v7, 31, v6
	v_lshlrev_b64 v[6:7], 13, v[6:7]
	v_lshl_add_u64 v[6:7], v[4:5], 0, v[6:7]
	global_load_dwordx4 v[34:37], v[6:7], off nt
	v_or_b32_e32 v6, 32, v2
	v_ashrrev_i32_e32 v7, 31, v6
	v_lshlrev_b64 v[6:7], 13, v[6:7]
	v_lshl_add_u64 v[6:7], v[4:5], 0, v[6:7]
	global_load_dwordx4 v[30:33], v[6:7], off nt
	v_or_b32_e32 v6, 36, v2
	v_ashrrev_i32_e32 v7, 31, v6
	v_lshlrev_b64 v[6:7], 13, v[6:7]
	v_lshl_add_u64 v[6:7], v[4:5], 0, v[6:7]
	global_load_dwordx4 v[26:29], v[6:7], off nt
	v_or_b32_e32 v6, 40, v2
	v_ashrrev_i32_e32 v7, 31, v6
	v_lshlrev_b64 v[6:7], 13, v[6:7]
	v_lshl_add_u64 v[6:7], v[4:5], 0, v[6:7]
	global_load_dwordx4 v[22:25], v[6:7], off nt
	v_or_b32_e32 v6, 44, v2
	v_ashrrev_i32_e32 v7, 31, v6
	v_lshlrev_b64 v[6:7], 13, v[6:7]
	v_lshl_add_u64 v[6:7], v[4:5], 0, v[6:7]
	global_load_dwordx4 v[18:21], v[6:7], off nt
	v_or_b32_e32 v6, 48, v2
	v_ashrrev_i32_e32 v7, 31, v6
	v_lshlrev_b64 v[6:7], 13, v[6:7]
	v_lshl_add_u64 v[6:7], v[4:5], 0, v[6:7]
	global_load_dwordx4 v[14:17], v[6:7], off nt
	v_or_b32_e32 v6, 52, v2
	v_ashrrev_i32_e32 v7, 31, v6
	v_lshlrev_b64 v[6:7], 13, v[6:7]
	v_lshl_add_u64 v[6:7], v[4:5], 0, v[6:7]
	global_load_dwordx4 v[10:13], v[6:7], off nt
	v_or_b32_e32 v6, 56, v2
	v_ashrrev_i32_e32 v7, 31, v6
	v_lshlrev_b64 v[6:7], 13, v[6:7]
	v_or_b32_e32 v2, 60, v2
	v_lshl_add_u64 v[6:7], v[4:5], 0, v[6:7]
	v_ashrrev_i32_e32 v3, 31, v2
	global_load_dwordx4 v[6:9], v[6:7], off nt
	v_lshlrev_b64 v[2:3], 13, v[2:3]
	v_lshl_add_u64 v[2:3], v[4:5], 0, v[2:3]
	global_load_dwordx4 v[2:5], v[2:3], off nt
	v_add_u32_e32 v67, 0x410, v99
	s_waitcnt vmcnt(0)
	ds_write2_b32 v99, v70, v71 offset1:1
	ds_write2_b32 v99, v72, v73 offset0:2 offset1:3
	s_ashr_i32 s5, s4, 31
	s_add_i32 s7, s7, s60
	s_add_i32 s6, s6, s33
	s_cmpk_lt_i32 s7, 0x400
	ds_write2_b32 v67, v58, v59 offset1:1
	v_add_u32_e32 v58, 0x418, v99
	ds_write2_b32 v58, v60, v61 offset1:1
	v_add_u32_e32 v58, 0x820, v99
	ds_write2_b32 v58, v54, v55 offset1:1
	v_add_u32_e32 v54, 0x828, v99
	ds_write2_b32 v54, v56, v57 offset1:1
	v_add_u32_e32 v54, 0xc30, v99
	ds_write2_b32 v54, v50, v51 offset1:1
	v_add_u32_e32 v50, 0xc38, v99
	ds_write2_b32 v50, v52, v53 offset1:1
	v_add_u32_e32 v50, 0x1040, v99
	ds_write2_b32 v50, v46, v47 offset1:1
	v_add_u32_e32 v46, 0x1048, v99
	ds_write2_b32 v46, v48, v49 offset1:1
	v_add_u32_e32 v46, 0x1450, v99
	ds_write2_b32 v46, v42, v43 offset1:1
	v_add_u32_e32 v42, 0x1458, v99
	ds_write2_b32 v42, v44, v45 offset1:1
	v_add_u32_e32 v42, 0x1860, v99
	ds_write2_b32 v42, v38, v39 offset1:1
	v_add_u32_e32 v38, 0x1868, v99
	ds_write2_b32 v38, v40, v41 offset1:1
	v_add_u32_e32 v38, 0x1c70, v99
	ds_write2_b32 v38, v34, v35 offset1:1
	v_add_u32_e32 v34, 0x1c78, v99
	ds_write2_b32 v34, v36, v37 offset1:1
	v_add_u32_e32 v34, 0x2080, v99
	ds_write2_b32 v34, v30, v31 offset1:1
	v_add_u32_e32 v30, 0x2088, v99
	ds_write2_b32 v30, v32, v33 offset1:1
	v_add_u32_e32 v30, 0x2490, v99
	ds_write2_b32 v30, v26, v27 offset1:1
	v_add_u32_e32 v26, 0x2498, v99
	ds_write2_b32 v26, v28, v29 offset1:1
	v_add_u32_e32 v26, 0x28a0, v99
	v_add_u32_e32 v28, 0x400, v101
	ds_write2_b32 v26, v22, v23 offset1:1
	v_add_u32_e32 v22, 0x28a8, v99
	ds_write2_b32 v22, v24, v25 offset1:1
	v_add_u32_e32 v22, 0x2cb0, v99
	v_add_u32_e32 v24, s2, v100
	ds_write2_b32 v22, v18, v19 offset1:1
	v_add_u32_e32 v18, 0x2cb8, v99
	ds_write2_b32 v18, v20, v21 offset1:1
	v_add_u32_e32 v18, 0x30c0, v99
	v_ashrrev_i32_e32 v25, 31, v24
	ds_write2_b32 v18, v14, v15 offset1:1
	v_add_u32_e32 v14, 0x30c8, v99
	ds_write2_b32 v14, v16, v17 offset1:1
	v_add_u32_e32 v14, 0x34d0, v99
	v_lshlrev_b64 v[26:27], 12, v[24:25]
	ds_write2_b32 v14, v10, v11 offset1:1
	v_add_u32_e32 v10, 0x34d8, v99
	ds_write2_b32 v10, v12, v13 offset1:1
	v_add_u32_e32 v10, 0x38e0, v99
	ds_write2_b32 v10, v6, v7 offset1:1
	v_add_u32_e32 v6, 0x38e8, v99
	ds_write2_b32 v6, v8, v9 offset1:1
	v_add_u32_e32 v6, 0x3cf0, v99
	ds_write2_b32 v6, v2, v3 offset1:1
	v_add_u32_e32 v2, 0x3cf8, v99
	ds_write2_b32 v2, v4, v5 offset1:1
	s_waitcnt lgkmcnt(0)
	ds_read2_b32 v[8:9], v101 offset0:65 offset1:73
	ds_read2_b32 v[10:11], v101 offset1:8
	ds_read2_b32 v[12:13], v101 offset0:130 offset1:138
	ds_read2_b32 v[14:15], v101 offset0:195 offset1:203
	ds_read2_b32 v[16:17], v28 offset0:4 offset1:12
	ds_read2_b32 v[18:19], v28 offset0:69 offset1:77
	ds_read2_b32 v[20:21], v28 offset0:134 offset1:142
	ds_read2_b32 v[22:23], v28 offset0:199 offset1:207
	v_lshl_add_u64 v[6:7], s[4:5], 1, v[64:65]
	s_waitcnt lgkmcnt(6)
	v_cvt_pk_bf16_f32 v2, v10, v8
	s_waitcnt lgkmcnt(4)
	v_cvt_pk_bf16_f32 v3, v12, v14
	s_waitcnt lgkmcnt(2)
	v_cvt_pk_bf16_f32 v4, v16, v18
	s_waitcnt lgkmcnt(0)
	v_cvt_pk_bf16_f32 v5, v20, v22
	v_lshl_add_u64 v[26:27], v[6:7], 0, v[26:27]
	v_add_u32_e32 v8, 8, v24
	global_store_dwordx4 v[26:27], v[2:5], off
	v_add_u32_e32 v26, 16, v24
	v_ashrrev_i32_e32 v27, 31, v26
	v_cvt_pk_bf16_f32 v2, v11, v9
	v_ashrrev_i32_e32 v9, 31, v8
	v_lshlrev_b64 v[8:9], 12, v[8:9]
	v_cvt_pk_bf16_f32 v3, v13, v15
	v_cvt_pk_bf16_f32 v4, v17, v19
	v_cvt_pk_bf16_f32 v5, v21, v23
	v_lshl_add_u64 v[8:9], v[6:7], 0, v[8:9]
	global_store_dwordx4 v[8:9], v[2:5], off
	ds_read2_b32 v[8:9], v101 offset0:81 offset1:89
	ds_read2_b32 v[10:11], v101 offset0:16 offset1:24
	ds_read2_b32 v[12:13], v101 offset0:146 offset1:154
	ds_read2_b32 v[14:15], v101 offset0:211 offset1:219
	ds_read2_b32 v[16:17], v28 offset0:20 offset1:28
	ds_read2_b32 v[18:19], v28 offset0:85 offset1:93
	ds_read2_b32 v[20:21], v28 offset0:150 offset1:158
	ds_read2_b32 v[22:23], v28 offset0:215 offset1:223
	v_lshlrev_b64 v[26:27], 12, v[26:27]
	s_waitcnt lgkmcnt(6)
	v_cvt_pk_bf16_f32 v2, v10, v8
	s_waitcnt lgkmcnt(4)
	v_cvt_pk_bf16_f32 v3, v12, v14
	s_waitcnt lgkmcnt(2)
	v_cvt_pk_bf16_f32 v4, v16, v18
	s_waitcnt lgkmcnt(0)
	v_cvt_pk_bf16_f32 v5, v20, v22
	v_lshl_add_u64 v[26:27], v[6:7], 0, v[26:27]
	v_add_u32_e32 v8, 24, v24
	global_store_dwordx4 v[26:27], v[2:5], off
	v_add_u32_e32 v26, 32, v24
	v_ashrrev_i32_e32 v27, 31, v26
	v_cvt_pk_bf16_f32 v2, v11, v9
	v_ashrrev_i32_e32 v9, 31, v8
	v_lshlrev_b64 v[8:9], 12, v[8:9]
	v_cvt_pk_bf16_f32 v3, v13, v15
	v_cvt_pk_bf16_f32 v4, v17, v19
	v_cvt_pk_bf16_f32 v5, v21, v23
	v_lshl_add_u64 v[8:9], v[6:7], 0, v[8:9]
	global_store_dwordx4 v[8:9], v[2:5], off
	ds_read2_b32 v[8:9], v101 offset0:32 offset1:40
	ds_read2_b32 v[10:11], v101 offset0:97 offset1:105
	ds_read2_b32 v[12:13], v101 offset0:162 offset1:170
	ds_read2_b32 v[14:15], v101 offset0:227 offset1:235
	ds_read2_b32 v[16:17], v28 offset0:36 offset1:44
	ds_read2_b32 v[18:19], v28 offset0:101 offset1:109
	ds_read2_b32 v[20:21], v28 offset0:166 offset1:174
	ds_read2_b32 v[22:23], v28 offset0:231 offset1:239
	v_lshlrev_b64 v[26:27], 12, v[26:27]
	s_waitcnt lgkmcnt(6)
	v_cvt_pk_bf16_f32 v2, v8, v10
	s_waitcnt lgkmcnt(4)
	v_cvt_pk_bf16_f32 v3, v12, v14
	s_waitcnt lgkmcnt(2)
	v_cvt_pk_bf16_f32 v4, v16, v18
	s_waitcnt lgkmcnt(0)
	v_cvt_pk_bf16_f32 v5, v20, v22
	v_lshl_add_u64 v[26:27], v[6:7], 0, v[26:27]
	v_add_u32_e32 v8, 40, v24
	global_store_dwordx4 v[26:27], v[2:5], off
	v_add_u32_e32 v26, 48, v24
	v_ashrrev_i32_e32 v27, 31, v26
	v_cvt_pk_bf16_f32 v2, v9, v11
	v_ashrrev_i32_e32 v9, 31, v8
	v_lshlrev_b64 v[8:9], 12, v[8:9]
	v_cvt_pk_bf16_f32 v3, v13, v15
	v_cvt_pk_bf16_f32 v4, v17, v19
	v_cvt_pk_bf16_f32 v5, v21, v23
	v_lshl_add_u64 v[8:9], v[6:7], 0, v[8:9]
	global_store_dwordx4 v[8:9], v[2:5], off
	ds_read2_b32 v[8:9], v101 offset0:48 offset1:56
	ds_read2_b32 v[10:11], v101 offset0:113 offset1:121
	ds_read2_b32 v[12:13], v101 offset0:178 offset1:186
	ds_read2_b32 v[14:15], v101 offset0:243 offset1:251
	ds_read2_b32 v[16:17], v28 offset0:52 offset1:60
	ds_read2_b32 v[18:19], v28 offset0:117 offset1:125
	ds_read2_b32 v[20:21], v28 offset0:182 offset1:190
	ds_read2_b32 v[22:23], v28 offset0:247 offset1:255
	v_lshlrev_b64 v[26:27], 12, v[26:27]
	s_waitcnt lgkmcnt(6)
	v_cvt_pk_bf16_f32 v2, v8, v10
	s_waitcnt lgkmcnt(4)
	v_cvt_pk_bf16_f32 v3, v12, v14
	s_waitcnt lgkmcnt(2)
	v_cvt_pk_bf16_f32 v4, v16, v18
	s_waitcnt lgkmcnt(0)
	v_cvt_pk_bf16_f32 v5, v20, v22
	v_lshl_add_u64 v[26:27], v[6:7], 0, v[26:27]
	v_add_u32_e32 v8, 56, v24
	global_store_dwordx4 v[26:27], v[2:5], off
	s_nop 1
	v_cvt_pk_bf16_f32 v2, v9, v11
	v_ashrrev_i32_e32 v9, 31, v8
	v_lshlrev_b64 v[8:9], 12, v[8:9]
	v_cvt_pk_bf16_f32 v3, v13, v15
	v_cvt_pk_bf16_f32 v4, v17, v19
	v_cvt_pk_bf16_f32 v5, v21, v23
	v_lshl_add_u64 v[6:7], v[6:7], 0, v[8:9]
	global_store_dwordx4 v[6:7], v[2:5], off
	s_waitcnt lgkmcnt(0)
	s_cbranch_scc1 .LBB0_414

.LBB0_418:
	s_ashr_i32 s2, s9, 31
	s_lshr_b32 s2, s2, 26
	s_add_i32 s2, s9, s2
	s_lshl_b32 s3, s2, 6
	s_andn2_b32 s2, s2, 63
	s_and_b32 s3, s3, 0xfffff000
	v_or_b32_e32 v74, s2, v1
	s_sub_i32 s4, s8, s3
	v_or_b32_e32 v6, 4, v74
	s_ashr_i32 s5, s4, 31
	v_ashrrev_i32_e32 v75, 31, v74
	v_ashrrev_i32_e32 v7, 31, v6
	v_lshl_add_u64 v[2:3], s[4:5], 2, v[70:71]
	v_lshlrev_b64 v[4:5], 14, v[74:75]
	v_lshlrev_b64 v[6:7], 14, v[6:7]
	v_lshl_add_u64 v[4:5], v[2:3], 0, v[4:5]
	v_lshl_add_u64 v[6:7], v[2:3], 0, v[6:7]
	global_load_dwordx4 v[62:65], v[4:5], off nt
	global_load_dwordx4 v[58:61], v[6:7], off nt
	v_or_b32_e32 v4, 8, v74
	v_or_b32_e32 v6, 12, v74
	v_ashrrev_i32_e32 v5, 31, v4
	v_ashrrev_i32_e32 v7, 31, v6
	v_lshlrev_b64 v[4:5], 14, v[4:5]
	v_lshlrev_b64 v[6:7], 14, v[6:7]
	v_lshl_add_u64 v[4:5], v[2:3], 0, v[4:5]
	v_lshl_add_u64 v[6:7], v[2:3], 0, v[6:7]
	global_load_dwordx4 v[54:57], v[4:5], off nt
	global_load_dwordx4 v[50:53], v[6:7], off nt
	v_or_b32_e32 v4, 16, v74
	v_or_b32_e32 v6, 20, v74
	v_ashrrev_i32_e32 v5, 31, v4
	v_ashrrev_i32_e32 v7, 31, v6
	v_lshlrev_b64 v[4:5], 14, v[4:5]
	v_lshlrev_b64 v[6:7], 14, v[6:7]
	v_lshl_add_u64 v[4:5], v[2:3], 0, v[4:5]
	v_lshl_add_u64 v[6:7], v[2:3], 0, v[6:7]
	global_load_dwordx4 v[46:49], v[4:5], off nt
	global_load_dwordx4 v[42:45], v[6:7], off nt
	v_or_b32_e32 v4, 24, v74
	v_or_b32_e32 v6, 28, v74
	v_ashrrev_i32_e32 v5, 31, v4
	v_ashrrev_i32_e32 v7, 31, v6
	v_lshlrev_b64 v[4:5], 14, v[4:5]
	v_lshlrev_b64 v[6:7], 14, v[6:7]
	v_lshl_add_u64 v[4:5], v[2:3], 0, v[4:5]
	v_lshl_add_u64 v[6:7], v[2:3], 0, v[6:7]
	global_load_dwordx4 v[38:41], v[4:5], off nt
	global_load_dwordx4 v[34:37], v[6:7], off nt
	v_or_b32_e32 v4, 32, v74
	v_or_b32_e32 v6, 36, v74
	v_ashrrev_i32_e32 v5, 31, v4
	v_ashrrev_i32_e32 v7, 31, v6
	v_lshlrev_b64 v[4:5], 14, v[4:5]
	v_lshlrev_b64 v[6:7], 14, v[6:7]
	v_lshl_add_u64 v[4:5], v[2:3], 0, v[4:5]
	v_lshl_add_u64 v[6:7], v[2:3], 0, v[6:7]
	global_load_dwordx4 v[30:33], v[4:5], off nt
	global_load_dwordx4 v[26:29], v[6:7], off nt
	v_or_b32_e32 v4, 40, v74
	v_or_b32_e32 v6, 44, v74
	v_ashrrev_i32_e32 v5, 31, v4
	v_ashrrev_i32_e32 v7, 31, v6
	v_lshlrev_b64 v[4:5], 14, v[4:5]
	v_lshlrev_b64 v[6:7], 14, v[6:7]
	v_lshl_add_u64 v[4:5], v[2:3], 0, v[4:5]
	v_lshl_add_u64 v[6:7], v[2:3], 0, v[6:7]
	global_load_dwordx4 v[22:25], v[4:5], off nt
	global_load_dwordx4 v[18:21], v[6:7], off nt
	v_or_b32_e32 v4, 48, v74
	v_or_b32_e32 v6, 52, v74
	v_ashrrev_i32_e32 v5, 31, v4
	v_ashrrev_i32_e32 v7, 31, v6
	v_lshlrev_b64 v[4:5], 14, v[4:5]
	v_lshlrev_b64 v[6:7], 14, v[6:7]
	v_lshl_add_u64 v[4:5], v[2:3], 0, v[4:5]
	v_lshl_add_u64 v[6:7], v[2:3], 0, v[6:7]
	global_load_dwordx4 v[14:17], v[4:5], off nt
	global_load_dwordx4 v[10:13], v[6:7], off nt
	v_or_b32_e32 v4, 56, v74
	v_or_b32_e32 v6, 60, v74
	v_ashrrev_i32_e32 v5, 31, v4
	v_ashrrev_i32_e32 v7, 31, v6
	v_lshlrev_b64 v[4:5], 14, v[4:5]
	v_lshlrev_b64 v[6:7], 14, v[6:7]
	v_lshl_add_u64 v[4:5], v[2:3], 0, v[4:5]
	v_lshl_add_u64 v[2:3], v[2:3], 0, v[6:7]
	global_load_dwordx4 v[6:9], v[4:5], off nt
	s_nop 0
	global_load_dwordx4 v[2:5], v[2:3], off nt
	v_readlane_b32 s36, v251, 12
	v_cndmask_b32_e64 v67, 0, 1, s[22:23]
	v_readlane_b32 s48, v251, 24
	v_readlane_b32 s49, v251, 25
	v_cmp_ne_u32_e64 s[4:5], 1, v67
	s_andn2_b64 vcc, exec, s[22:23]
	v_lshl_add_u64 v[74:75], v[74:75], 2, s[48:49]
	v_readlane_b32 s37, v251, 13
	v_readlane_b32 s38, v251, 14
	v_readlane_b32 s39, v251, 15
	v_readlane_b32 s40, v251, 16
	v_readlane_b32 s41, v251, 17
	v_readlane_b32 s42, v251, 18
	v_readlane_b32 s43, v251, 19
	v_readlane_b32 s44, v251, 20
	v_readlane_b32 s45, v251, 21
	v_readlane_b32 s46, v251, 22
	v_readlane_b32 s47, v251, 23
	v_readlane_b32 s50, v251, 26
	v_readlane_b32 s51, v251, 27
	s_cbranch_vccnz .LBB0_441
	global_load_dword v78, v[74:75], off
	global_load_dword v76, v[74:75], off offset:16
	s_waitcnt vmcnt(0)
	v_pk_mul_f32 v[80:81], v[62:63], v[78:79] op_sel_hi:[1,0]
	v_pk_mul_f32 v[78:79], v[64:65], v[78:79] op_sel_hi:[1,0]
	ds_write2_b32 v99, v80, v81 offset1:1
	ds_write2_b32 v99, v78, v79 offset0:2 offset1:3
	s_cbranch_execnz .LBB0_421

.LBB0_452:
	s_ashr_i32 s0, s5, 31
	s_lshr_b32 s0, s0, 27
	s_add_i32 s0, s5, s0
	s_ashr_i32 s1, s0, 5
	s_lshl_b32 s0, s1, 11
	s_lshl_b32 s2, s1, 6
	s_sub_i32 s0, s4, s0
	v_or_b32_e32 v106, s2, v1
	s_ashr_i32 s1, s0, 31
	v_ashrrev_i32_e32 v107, 31, v106
	v_lshl_add_u64 v[2:3], s[0:1], 2, v[62:63]
	v_lshlrev_b64 v[4:5], 13, v[106:107]
	v_lshl_add_u64 v[4:5], v[2:3], 0, v[4:5]
	v_or_b32_e32 v108, 4, v106
	v_or_b32_e32 v96, 8, v106
	v_or_b32_e32 v94, 12, v106
	v_or_b32_e32 v92, 16, v106
	v_or_b32_e32 v90, 20, v106
	v_or_b32_e32 v88, 24, v106
	v_or_b32_e32 v86, 28, v106
	v_or_b32_e32 v84, 32, v106
	v_or_b32_e32 v82, 36, v106
	v_or_b32_e32 v80, 40, v106
	v_or_b32_e32 v78, 44, v106
	v_or_b32_e32 v76, 48, v106
	v_or_b32_e32 v74, 52, v106
	v_or_b32_e32 v72, 56, v106
	v_or_b32_e32 v70, 60, v106
	v_lshl_add_u64 v[106:107], v[106:107], 2, s[92:93]
	global_load_dwordx4 v[102:105], v[4:5], off nt
	global_load_dword v98, v[106:107], off
	v_ashrrev_i32_e32 v109, 31, v108
	v_lshlrev_b64 v[4:5], 13, v[108:109]
	v_lshl_add_u64 v[4:5], v[2:3], 0, v[4:5]
	global_load_dwordx4 v[58:61], v[4:5], off nt
	v_ashrrev_i32_e32 v97, 31, v96
	v_lshlrev_b64 v[4:5], 13, v[96:97]
	v_lshl_add_u64 v[4:5], v[2:3], 0, v[4:5]
	global_load_dwordx4 v[54:57], v[4:5], off nt
	v_ashrrev_i32_e32 v95, 31, v94
	v_lshlrev_b64 v[4:5], 13, v[94:95]
	v_lshl_add_u64 v[4:5], v[2:3], 0, v[4:5]
	global_load_dwordx4 v[50:53], v[4:5], off nt
	v_ashrrev_i32_e32 v93, 31, v92
	v_lshlrev_b64 v[4:5], 13, v[92:93]
	v_lshl_add_u64 v[4:5], v[2:3], 0, v[4:5]
	global_load_dwordx4 v[46:49], v[4:5], off nt
	v_ashrrev_i32_e32 v91, 31, v90
	v_lshlrev_b64 v[4:5], 13, v[90:91]
	v_lshl_add_u64 v[4:5], v[2:3], 0, v[4:5]
	global_load_dwordx4 v[42:45], v[4:5], off nt
	v_ashrrev_i32_e32 v89, 31, v88
	v_lshlrev_b64 v[4:5], 13, v[88:89]
	v_lshl_add_u64 v[4:5], v[2:3], 0, v[4:5]
	global_load_dwordx4 v[38:41], v[4:5], off nt
	v_ashrrev_i32_e32 v87, 31, v86
	v_lshlrev_b64 v[4:5], 13, v[86:87]
	v_lshl_add_u64 v[4:5], v[2:3], 0, v[4:5]
	global_load_dwordx4 v[34:37], v[4:5], off nt
	v_ashrrev_i32_e32 v85, 31, v84
	v_lshlrev_b64 v[4:5], 13, v[84:85]
	v_lshl_add_u64 v[4:5], v[2:3], 0, v[4:5]
	global_load_dwordx4 v[30:33], v[4:5], off nt
	v_ashrrev_i32_e32 v83, 31, v82
	v_lshlrev_b64 v[4:5], 13, v[82:83]
	v_lshl_add_u64 v[4:5], v[2:3], 0, v[4:5]
	global_load_dwordx4 v[26:29], v[4:5], off nt
	v_ashrrev_i32_e32 v81, 31, v80
	v_lshlrev_b64 v[4:5], 13, v[80:81]
	v_lshl_add_u64 v[4:5], v[2:3], 0, v[4:5]
	global_load_dwordx4 v[22:25], v[4:5], off nt
	v_ashrrev_i32_e32 v79, 31, v78
	v_lshlrev_b64 v[4:5], 13, v[78:79]
	v_lshl_add_u64 v[4:5], v[2:3], 0, v[4:5]
	global_load_dwordx4 v[18:21], v[4:5], off nt
	v_ashrrev_i32_e32 v77, 31, v76
	v_lshlrev_b64 v[4:5], 13, v[76:77]
	v_lshl_add_u64 v[4:5], v[2:3], 0, v[4:5]
	global_load_dwordx4 v[14:17], v[4:5], off nt
	v_ashrrev_i32_e32 v75, 31, v74
	v_lshlrev_b64 v[4:5], 13, v[74:75]
	v_lshl_add_u64 v[4:5], v[2:3], 0, v[4:5]
	global_load_dwordx4 v[10:13], v[4:5], off nt
	v_ashrrev_i32_e32 v73, 31, v72
	v_lshlrev_b64 v[4:5], 13, v[72:73]
	v_lshl_add_u64 v[4:5], v[2:3], 0, v[4:5]
	global_load_dwordx4 v[6:9], v[4:5], off nt
	v_ashrrev_i32_e32 v71, 31, v70
	v_lshlrev_b64 v[4:5], 13, v[70:71]
	v_lshl_add_u64 v[2:3], v[2:3], 0, v[4:5]
	global_load_dwordx4 v[2:5], v[2:3], off nt
	s_ashr_i32 s3, s2, 31
	s_add_i32 s5, s5, s60
	s_add_i32 s4, s4, s33
	s_cmpk_lt_i32 s5, 0x400
	s_waitcnt vmcnt(0)
	v_pk_mul_f32 v[102:103], v[102:103], v[98:99] op_sel_hi:[1,0]
	ds_write2_b32 v99, v102, v103 offset1:1
	v_pk_mul_f32 v[102:103], v[104:105], v[98:99] op_sel_hi:[1,0]
	ds_write2_b32 v99, v102, v103 offset0:2 offset1:3
	v_lshl_add_u64 v[102:103], v[108:109], 2, s[92:93]
	global_load_dword v98, v[102:103], off
	v_add_u32_e32 v102, 0x410, v99
	s_waitcnt vmcnt(0)
	v_pk_mul_f32 v[58:59], v[58:59], v[98:99] op_sel_hi:[1,0]
	ds_write2_b32 v102, v58, v59 offset1:1
	v_pk_mul_f32 v[60:61], v[60:61], v[98:99] op_sel_hi:[1,0]
	v_add_u32_e32 v58, 0x418, v99
	ds_write2_b32 v58, v60, v61 offset1:1
	v_lshl_add_u64 v[60:61], v[96:97], 2, s[92:93]
	global_load_dword v60, v[60:61], off
	s_waitcnt vmcnt(0)
	v_pk_mul_f32 v[96:97], v[54:55], v[60:61] op_sel_hi:[1,0]
	v_pk_mul_f32 v[56:57], v[56:57], v[60:61] op_sel_hi:[1,0]
	v_add_u32_e32 v55, 0x828, v99
	ds_write2_b32 v55, v56, v57 offset1:1
	v_lshl_add_u64 v[56:57], v[94:95], 2, s[92:93]
	global_load_dword v56, v[56:57], off
	v_add_u32_e32 v54, 0x820, v99
	ds_write2_b32 v54, v96, v97 offset1:1
	s_waitcnt vmcnt(0)
	v_pk_mul_f32 v[60:61], v[50:51], v[56:57] op_sel_hi:[1,0]
	v_pk_mul_f32 v[52:53], v[52:53], v[56:57] op_sel_hi:[1,0]
	v_add_u32_e32 v51, 0xc38, v99
	ds_write2_b32 v51, v52, v53 offset1:1
	v_lshl_add_u64 v[52:53], v[92:93], 2, s[92:93]
	global_load_dword v52, v[52:53], off
	v_add_u32_e32 v50, 0xc30, v99
	ds_write2_b32 v50, v60, v61 offset1:1
	s_waitcnt vmcnt(0)
	v_pk_mul_f32 v[56:57], v[46:47], v[52:53] op_sel_hi:[1,0]
	v_pk_mul_f32 v[48:49], v[48:49], v[52:53] op_sel_hi:[1,0]
	v_add_u32_e32 v47, 0x1048, v99
	ds_write2_b32 v47, v48, v49 offset1:1
	v_lshl_add_u64 v[48:49], v[90:91], 2, s[92:93]
	global_load_dword v48, v[48:49], off
	v_add_u32_e32 v46, 0x1040, v99
	ds_write2_b32 v46, v56, v57 offset1:1
	s_waitcnt vmcnt(0)
	v_pk_mul_f32 v[52:53], v[42:43], v[48:49] op_sel_hi:[1,0]
	v_pk_mul_f32 v[44:45], v[44:45], v[48:49] op_sel_hi:[1,0]
	v_add_u32_e32 v43, 0x1458, v99
	ds_write2_b32 v43, v44, v45 offset1:1
	v_lshl_add_u64 v[44:45], v[88:89], 2, s[92:93]
	global_load_dword v44, v[44:45], off
	v_add_u32_e32 v42, 0x1450, v99
	ds_write2_b32 v42, v52, v53 offset1:1
	s_waitcnt vmcnt(0)
	v_pk_mul_f32 v[48:49], v[38:39], v[44:45] op_sel_hi:[1,0]
	v_pk_mul_f32 v[40:41], v[40:41], v[44:45] op_sel_hi:[1,0]
	v_add_u32_e32 v39, 0x1868, v99
	ds_write2_b32 v39, v40, v41 offset1:1
	v_lshl_add_u64 v[40:41], v[86:87], 2, s[92:93]
	global_load_dword v40, v[40:41], off
	v_add_u32_e32 v38, 0x1860, v99
	ds_write2_b32 v38, v48, v49 offset1:1
	v_add_u32_e32 v48, s0, v100
	v_ashrrev_i32_e32 v49, 31, v48
	v_lshlrev_b64 v[52:53], 12, v[48:49]
	v_add_u32_e32 v56, 16, v48
	v_ashrrev_i32_e32 v57, 31, v56
	v_lshlrev_b64 v[56:57], 12, v[56:57]
	s_waitcnt vmcnt(0)
	v_pk_mul_f32 v[44:45], v[34:35], v[40:41] op_sel_hi:[1,0]
	v_pk_mul_f32 v[36:37], v[36:37], v[40:41] op_sel_hi:[1,0]
	v_add_u32_e32 v35, 0x1c78, v99
	ds_write2_b32 v35, v36, v37 offset1:1
	v_lshl_add_u64 v[36:37], v[84:85], 2, s[92:93]
	global_load_dword v36, v[36:37], off
	v_add_u32_e32 v34, 0x1c70, v99
	ds_write2_b32 v34, v44, v45 offset1:1
	s_waitcnt vmcnt(0)
	v_pk_mul_f32 v[40:41], v[30:31], v[36:37] op_sel_hi:[1,0]
	v_pk_mul_f32 v[32:33], v[32:33], v[36:37] op_sel_hi:[1,0]
	v_add_u32_e32 v31, 0x2088, v99
	ds_write2_b32 v31, v32, v33 offset1:1
	v_lshl_add_u64 v[32:33], v[82:83], 2, s[92:93]
	global_load_dword v32, v[32:33], off
	v_add_u32_e32 v30, 0x2080, v99
	ds_write2_b32 v30, v40, v41 offset1:1
	s_waitcnt vmcnt(0)
	v_pk_mul_f32 v[36:37], v[26:27], v[32:33] op_sel_hi:[1,0]
	v_pk_mul_f32 v[28:29], v[28:29], v[32:33] op_sel_hi:[1,0]
	v_add_u32_e32 v27, 0x2498, v99
	ds_write2_b32 v27, v28, v29 offset1:1
	v_lshl_add_u64 v[28:29], v[80:81], 2, s[92:93]
	global_load_dword v28, v[28:29], off
	v_add_u32_e32 v26, 0x2490, v99
	ds_write2_b32 v26, v36, v37 offset1:1
	s_waitcnt vmcnt(0)
	v_pk_mul_f32 v[32:33], v[22:23], v[28:29] op_sel_hi:[1,0]
	v_pk_mul_f32 v[24:25], v[24:25], v[28:29] op_sel_hi:[1,0]
	v_add_u32_e32 v23, 0x28a8, v99
	ds_write2_b32 v23, v24, v25 offset1:1
	v_lshl_add_u64 v[24:25], v[78:79], 2, s[92:93]
	global_load_dword v24, v[24:25], off
	v_add_u32_e32 v22, 0x28a0, v99
	ds_write2_b32 v22, v32, v33 offset1:1
	s_waitcnt vmcnt(0)
	v_pk_mul_f32 v[28:29], v[18:19], v[24:25] op_sel_hi:[1,0]
	v_pk_mul_f32 v[20:21], v[20:21], v[24:25] op_sel_hi:[1,0]
	v_add_u32_e32 v19, 0x2cb8, v99
	ds_write2_b32 v19, v20, v21 offset1:1
	v_lshl_add_u64 v[20:21], v[76:77], 2, s[92:93]
	global_load_dword v20, v[20:21], off
	v_add_u32_e32 v18, 0x2cb0, v99
	ds_write2_b32 v18, v28, v29 offset1:1
	s_waitcnt vmcnt(0)
	v_pk_mul_f32 v[24:25], v[14:15], v[20:21] op_sel_hi:[1,0]
	v_pk_mul_f32 v[16:17], v[16:17], v[20:21] op_sel_hi:[1,0]
	v_add_u32_e32 v15, 0x30c8, v99
	ds_write2_b32 v15, v16, v17 offset1:1
	v_lshl_add_u64 v[16:17], v[74:75], 2, s[92:93]
	global_load_dword v16, v[16:17], off
	v_add_u32_e32 v14, 0x30c0, v99
	ds_write2_b32 v14, v24, v25 offset1:1
	s_waitcnt vmcnt(0)
	v_pk_mul_f32 v[20:21], v[10:11], v[16:17] op_sel_hi:[1,0]
	v_pk_mul_f32 v[12:13], v[12:13], v[16:17] op_sel_hi:[1,0]
	v_add_u32_e32 v11, 0x34d8, v99
	ds_write2_b32 v11, v12, v13 offset1:1
	v_lshl_add_u64 v[12:13], v[72:73], 2, s[92:93]
	global_load_dword v12, v[12:13], off
	v_add_u32_e32 v10, 0x34d0, v99
	ds_write2_b32 v10, v20, v21 offset1:1
	s_waitcnt vmcnt(0)
	v_pk_mul_f32 v[16:17], v[6:7], v[12:13] op_sel_hi:[1,0]
	v_pk_mul_f32 v[8:9], v[8:9], v[12:13] op_sel_hi:[1,0]
	v_add_u32_e32 v7, 0x38e8, v99
	ds_write2_b32 v7, v8, v9 offset1:1
	v_lshl_add_u64 v[8:9], v[70:71], 2, s[92:93]
	global_load_dword v12, v[8:9], off
	v_add_u32_e32 v8, 0x3cf0, v99
	v_add_u32_e32 v6, 0x38e0, v99
	v_add_u32_e32 v9, 0x3cf8, v99
	ds_write2_b32 v6, v16, v17 offset1:1
	v_lshl_add_u64 v[16:17], s[2:3], 1, v[64:65]
	v_lshl_add_u64 v[52:53], v[16:17], 0, v[52:53]
	v_lshl_add_u64 v[56:57], v[16:17], 0, v[56:57]
	s_waitcnt vmcnt(0)
	v_pk_mul_f32 v[2:3], v[2:3], v[12:13] op_sel_hi:[1,0]
	ds_write2_b32 v8, v2, v3 offset1:1
	v_pk_mul_f32 v[2:3], v[4:5], v[12:13] op_sel_hi:[1,0]
	ds_write2_b32 v9, v2, v3 offset1:1
	s_waitcnt lgkmcnt(0)
	ds_read2_b32 v[12:13], v101 offset0:65 offset1:73
	ds_read2_b32 v[20:21], v101 offset1:8
	ds_read2_b32 v[24:25], v101 offset0:130 offset1:138
	ds_read2_b32 v[28:29], v101 offset0:195 offset1:203
	s_waitcnt lgkmcnt(2)
	v_cvt_pk_bf16_f32 v2, v20, v12
	v_add_u32_e32 v12, 0x400, v101
	ds_read2_b32 v[32:33], v12 offset0:4 offset1:12
	ds_read2_b32 v[36:37], v12 offset0:69 offset1:77
	ds_read2_b32 v[40:41], v12 offset0:134 offset1:142
	ds_read2_b32 v[44:45], v12 offset0:199 offset1:207
	s_waitcnt lgkmcnt(4)
	v_cvt_pk_bf16_f32 v3, v24, v28
	v_add_u32_e32 v20, 8, v48
	s_waitcnt lgkmcnt(2)
	v_cvt_pk_bf16_f32 v4, v32, v36
	s_waitcnt lgkmcnt(0)
	v_cvt_pk_bf16_f32 v5, v40, v44
	global_store_dwordx4 v[52:53], v[2:5], off
	s_nop 1
	v_cvt_pk_bf16_f32 v2, v21, v13
	v_ashrrev_i32_e32 v21, 31, v20
	v_lshlrev_b64 v[20:21], 12, v[20:21]
	v_cvt_pk_bf16_f32 v3, v25, v29
	v_cvt_pk_bf16_f32 v4, v33, v37
	v_cvt_pk_bf16_f32 v5, v41, v45
	v_lshl_add_u64 v[20:21], v[16:17], 0, v[20:21]
	global_store_dwordx4 v[20:21], v[2:5], off
	ds_read2_b32 v[20:21], v101 offset0:81 offset1:89
	ds_read2_b32 v[24:25], v101 offset0:16 offset1:24
	ds_read2_b32 v[28:29], v101 offset0:146 offset1:154
	ds_read2_b32 v[32:33], v101 offset0:211 offset1:219
	ds_read2_b32 v[36:37], v12 offset0:20 offset1:28
	ds_read2_b32 v[40:41], v12 offset0:85 offset1:93
	ds_read2_b32 v[44:45], v12 offset0:150 offset1:158
	ds_read2_b32 v[52:53], v12 offset0:215 offset1:223
	s_waitcnt lgkmcnt(6)
	v_cvt_pk_bf16_f32 v2, v24, v20
	s_waitcnt lgkmcnt(4)
	v_cvt_pk_bf16_f32 v3, v28, v32
	s_waitcnt lgkmcnt(2)
	v_cvt_pk_bf16_f32 v4, v36, v40
	s_waitcnt lgkmcnt(0)
	v_cvt_pk_bf16_f32 v5, v44, v52
	v_add_u32_e32 v20, 24, v48
	global_store_dwordx4 v[56:57], v[2:5], off
	v_add_u32_e32 v56, 32, v48
	v_ashrrev_i32_e32 v57, 31, v56
	v_cvt_pk_bf16_f32 v2, v25, v21
	v_ashrrev_i32_e32 v21, 31, v20
	v_lshlrev_b64 v[20:21], 12, v[20:21]
	v_cvt_pk_bf16_f32 v3, v29, v33
	v_cvt_pk_bf16_f32 v4, v37, v41
	v_cvt_pk_bf16_f32 v5, v45, v53
	v_lshl_add_u64 v[20:21], v[16:17], 0, v[20:21]
	global_store_dwordx4 v[20:21], v[2:5], off
	ds_read2_b32 v[20:21], v101 offset0:32 offset1:40
	ds_read2_b32 v[24:25], v101 offset0:97 offset1:105
	ds_read2_b32 v[28:29], v101 offset0:162 offset1:170
	ds_read2_b32 v[32:33], v101 offset0:227 offset1:235
	ds_read2_b32 v[36:37], v12 offset0:36 offset1:44
	ds_read2_b32 v[40:41], v12 offset0:101 offset1:109
	ds_read2_b32 v[44:45], v12 offset0:166 offset1:174
	ds_read2_b32 v[52:53], v12 offset0:231 offset1:239
	v_lshlrev_b64 v[56:57], 12, v[56:57]
	s_waitcnt lgkmcnt(6)
	v_cvt_pk_bf16_f32 v2, v20, v24
	s_waitcnt lgkmcnt(4)
	v_cvt_pk_bf16_f32 v3, v28, v32
	s_waitcnt lgkmcnt(2)
	v_cvt_pk_bf16_f32 v4, v36, v40
	s_waitcnt lgkmcnt(0)
	v_cvt_pk_bf16_f32 v5, v44, v52
	v_lshl_add_u64 v[56:57], v[16:17], 0, v[56:57]
	v_add_u32_e32 v20, 40, v48
	global_store_dwordx4 v[56:57], v[2:5], off
	v_add_u32_e32 v56, 48, v48
	v_ashrrev_i32_e32 v57, 31, v56
	v_cvt_pk_bf16_f32 v2, v21, v25
	v_ashrrev_i32_e32 v21, 31, v20
	v_lshlrev_b64 v[20:21], 12, v[20:21]
	v_cvt_pk_bf16_f32 v3, v29, v33
	v_cvt_pk_bf16_f32 v4, v37, v41
	v_cvt_pk_bf16_f32 v5, v45, v53
	v_lshl_add_u64 v[20:21], v[16:17], 0, v[20:21]
	global_store_dwordx4 v[20:21], v[2:5], off
	ds_read2_b32 v[20:21], v101 offset0:48 offset1:56
	ds_read2_b32 v[24:25], v101 offset0:113 offset1:121
	ds_read2_b32 v[28:29], v101 offset0:178 offset1:186
	ds_read2_b32 v[32:33], v101 offset0:243 offset1:251
	ds_read2_b32 v[36:37], v12 offset0:52 offset1:60
	ds_read2_b32 v[40:41], v12 offset0:117 offset1:125
	ds_read2_b32 v[44:45], v12 offset0:182 offset1:190
	ds_read2_b32 v[52:53], v12 offset0:247 offset1:255
	v_lshlrev_b64 v[56:57], 12, v[56:57]
	s_waitcnt lgkmcnt(6)
	v_cvt_pk_bf16_f32 v2, v20, v24
	s_waitcnt lgkmcnt(4)
	v_cvt_pk_bf16_f32 v3, v28, v32
	s_waitcnt lgkmcnt(2)
	v_cvt_pk_bf16_f32 v4, v36, v40
	s_waitcnt lgkmcnt(0)
	v_cvt_pk_bf16_f32 v5, v44, v52
	v_lshl_add_u64 v[56:57], v[16:17], 0, v[56:57]
	v_add_u32_e32 v20, 56, v48
	global_store_dwordx4 v[56:57], v[2:5], off
	s_nop 1
	v_cvt_pk_bf16_f32 v2, v21, v25
	v_ashrrev_i32_e32 v21, 31, v20
	v_lshlrev_b64 v[20:21], 12, v[20:21]
	v_cvt_pk_bf16_f32 v3, v29, v33
	v_cvt_pk_bf16_f32 v4, v37, v41
	v_cvt_pk_bf16_f32 v5, v45, v53
	v_lshl_add_u64 v[16:17], v[16:17], 0, v[20:21]
	global_store_dwordx4 v[16:17], v[2:5], off
	s_waitcnt lgkmcnt(0)
	s_cbranch_scc1 .LBB0_452
	v_readlane_b32 s0, v252, 0
	v_readlane_b32 s1, v252, 1
	v_readlane_b32 s0, v252, 47
	v_mov_b32_e32 v69, v0
	v_readlane_b32 s6, v252, 6
	v_readlane_b32 s7, v252, 7
	v_mov_b32_e32 v67, v0
	v_readlane_b32 s1, v252, 48
	v_lshl_add_u64 v[2:3], s[6:7], 0, v[68:69]
	v_readlane_b32 s2, v252, 2
	v_lshl_add_u64 v[4:5], s[0:1], 0, v[66:67]
	v_readlane_b32 s3, v252, 3
	v_readlane_b32 s4, v252, 4
	v_readlane_b32 s5, v252, 5
.LBB0_454:
	s_ashr_i32 s0, s56, 31
	s_lshr_b32 s0, s0, 27
	s_add_i32 s0, s56, s0
	s_ashr_i32 s1, s0, 5
	s_lshl_b32 s0, s1, 11
	s_lshl_b32 s2, s1, 6
	s_sub_i32 s0, s12, s0
	v_or_b32_e32 v16, s2, v1
	s_ashr_i32 s1, s0, 31
	v_ashrrev_i32_e32 v17, 31, v16
	v_lshl_add_u64 v[20:21], s[0:1], 2, v[2:3]
	v_lshlrev_b64 v[24:25], 13, v[16:17]
	v_lshl_add_u64 v[24:25], v[20:21], 0, v[24:25]
	global_load_dwordx4 v[60:63], v[24:25], off nt
	v_or_b32_e32 v24, 4, v16
	v_ashrrev_i32_e32 v25, 31, v24
	v_lshlrev_b64 v[24:25], 13, v[24:25]
	v_lshl_add_u64 v[24:25], v[20:21], 0, v[24:25]
	global_load_dwordx4 v[64:67], v[24:25], off nt
	v_or_b32_e32 v24, 8, v16
	v_ashrrev_i32_e32 v25, 31, v24
	v_lshlrev_b64 v[24:25], 13, v[24:25]
	v_lshl_add_u64 v[24:25], v[20:21], 0, v[24:25]
	global_load_dwordx4 v[68:71], v[24:25], off nt
	v_or_b32_e32 v24, 12, v16
	v_ashrrev_i32_e32 v25, 31, v24
	v_lshlrev_b64 v[24:25], 13, v[24:25]
	v_lshl_add_u64 v[24:25], v[20:21], 0, v[24:25]
	global_load_dwordx4 v[72:75], v[24:25], off nt
	v_or_b32_e32 v24, 16, v16
	v_ashrrev_i32_e32 v25, 31, v24
	v_lshlrev_b64 v[24:25], 13, v[24:25]
	v_lshl_add_u64 v[24:25], v[20:21], 0, v[24:25]
	global_load_dwordx4 v[76:79], v[24:25], off nt
	v_or_b32_e32 v24, 20, v16
	v_ashrrev_i32_e32 v25, 31, v24
	v_lshlrev_b64 v[24:25], 13, v[24:25]
	v_lshl_add_u64 v[24:25], v[20:21], 0, v[24:25]
	global_load_dwordx4 v[80:83], v[24:25], off nt
	v_or_b32_e32 v24, 24, v16
	v_ashrrev_i32_e32 v25, 31, v24
	v_lshlrev_b64 v[24:25], 13, v[24:25]
	v_lshl_add_u64 v[24:25], v[20:21], 0, v[24:25]
	global_load_dwordx4 v[84:87], v[24:25], off nt
	v_or_b32_e32 v24, 28, v16
	v_ashrrev_i32_e32 v25, 31, v24
	v_lshlrev_b64 v[24:25], 13, v[24:25]
	v_lshl_add_u64 v[24:25], v[20:21], 0, v[24:25]
	global_load_dwordx4 v[88:91], v[24:25], off nt
	v_or_b32_e32 v24, 32, v16
	v_ashrrev_i32_e32 v25, 31, v24
	v_lshlrev_b64 v[24:25], 13, v[24:25]
	v_lshl_add_u64 v[24:25], v[20:21], 0, v[24:25]
	global_load_dwordx4 v[92:95], v[24:25], off nt
	v_or_b32_e32 v24, 36, v16
	v_ashrrev_i32_e32 v25, 31, v24
	v_lshlrev_b64 v[24:25], 13, v[24:25]
	v_lshl_add_u64 v[24:25], v[20:21], 0, v[24:25]
	global_load_dwordx4 v[104:107], v[24:25], off nt
	v_or_b32_e32 v24, 40, v16
	v_ashrrev_i32_e32 v25, 31, v24
	v_lshlrev_b64 v[24:25], 13, v[24:25]
	v_lshl_add_u64 v[24:25], v[20:21], 0, v[24:25]
	global_load_dwordx4 v[108:111], v[24:25], off nt
	v_or_b32_e32 v24, 44, v16
	v_ashrrev_i32_e32 v25, 31, v24
	v_lshlrev_b64 v[24:25], 13, v[24:25]
	v_lshl_add_u64 v[24:25], v[20:21], 0, v[24:25]
	global_load_dwordx4 v[112:115], v[24:25], off nt
	v_or_b32_e32 v24, 48, v16
	v_ashrrev_i32_e32 v25, 31, v24
	v_lshlrev_b64 v[24:25], 13, v[24:25]
	v_lshl_add_u64 v[24:25], v[20:21], 0, v[24:25]
	global_load_dwordx4 v[116:119], v[24:25], off nt
	v_or_b32_e32 v24, 52, v16
	v_ashrrev_i32_e32 v25, 31, v24
	v_lshlrev_b64 v[24:25], 13, v[24:25]
	v_lshl_add_u64 v[24:25], v[20:21], 0, v[24:25]
	global_load_dwordx4 v[120:123], v[24:25], off nt
	v_or_b32_e32 v24, 56, v16
	v_ashrrev_i32_e32 v25, 31, v24
	v_lshlrev_b64 v[24:25], 13, v[24:25]
	v_or_b32_e32 v16, 60, v16
	v_lshl_add_u64 v[24:25], v[20:21], 0, v[24:25]
	v_ashrrev_i32_e32 v17, 31, v16
	global_load_dwordx4 v[124:127], v[24:25], off nt
	v_lshlrev_b64 v[16:17], 13, v[16:17]
	v_lshl_add_u64 v[16:17], v[20:21], 0, v[16:17]
	global_load_dwordx4 v[128:131], v[16:17], off nt
	v_add_u32_e32 v52, s0, v100
	s_ashr_i32 s3, s2, 31
	v_ashrrev_i32_e32 v53, 31, v52
	v_lshl_add_u64 v[16:17], s[2:3], 1, v[4:5]
	v_lshlrev_b64 v[56:57], 12, v[52:53]
	v_lshl_add_u64 v[56:57], v[16:17], 0, v[56:57]
	s_add_i32 s56, s56, s60
	s_add_i32 s12, s12, s33
	s_cmpk_lt_i32 s56, 0x400
	s_waitcnt vmcnt(15)
	ds_write2_b32 v99, v60, v61 offset1:1
	ds_write2_b32 v99, v62, v63 offset0:2 offset1:3
	s_waitcnt vmcnt(14)
	ds_write2_b32 v102, v64, v65 offset1:1
	ds_write2_b32 v58, v66, v67 offset1:1
	s_waitcnt vmcnt(13)
	ds_write2_b32 v54, v68, v69 offset1:1
	ds_write2_b32 v55, v70, v71 offset1:1
	s_waitcnt vmcnt(12)
	ds_write2_b32 v50, v72, v73 offset1:1
	ds_write2_b32 v51, v74, v75 offset1:1
	s_waitcnt vmcnt(11)
	ds_write2_b32 v46, v76, v77 offset1:1
	ds_write2_b32 v47, v78, v79 offset1:1
	s_waitcnt vmcnt(10)
	ds_write2_b32 v42, v80, v81 offset1:1
	ds_write2_b32 v43, v82, v83 offset1:1
	s_waitcnt vmcnt(9)
	ds_write2_b32 v38, v84, v85 offset1:1
	ds_write2_b32 v39, v86, v87 offset1:1
	s_waitcnt vmcnt(8)
	ds_write2_b32 v34, v88, v89 offset1:1
	ds_write2_b32 v35, v90, v91 offset1:1
	s_waitcnt vmcnt(7)
	ds_write2_b32 v30, v92, v93 offset1:1
	ds_write2_b32 v31, v94, v95 offset1:1
	s_waitcnt vmcnt(6)
	ds_write2_b32 v26, v104, v105 offset1:1
	ds_write2_b32 v27, v106, v107 offset1:1
	s_waitcnt vmcnt(5)
	ds_write2_b32 v22, v108, v109 offset1:1
	ds_write2_b32 v23, v110, v111 offset1:1
	s_waitcnt vmcnt(4)
	ds_write2_b32 v18, v112, v113 offset1:1
	ds_write2_b32 v19, v114, v115 offset1:1
	s_waitcnt vmcnt(3)
	ds_write2_b32 v14, v116, v117 offset1:1
	ds_write2_b32 v15, v118, v119 offset1:1
	s_waitcnt vmcnt(2)
	ds_write2_b32 v10, v120, v121 offset1:1
	ds_write2_b32 v11, v122, v123 offset1:1
	s_waitcnt vmcnt(1)
	ds_write2_b32 v6, v124, v125 offset1:1
	ds_write2_b32 v7, v126, v127 offset1:1
	s_waitcnt vmcnt(0)
	ds_write2_b32 v8, v128, v129 offset1:1
	ds_write2_b32 v9, v130, v131 offset1:1
	s_waitcnt lgkmcnt(0)
	ds_read2_b32 v[20:21], v101 offset0:65 offset1:73
	ds_read2_b32 v[24:25], v101 offset1:8
	ds_read2_b32 v[28:29], v101 offset0:130 offset1:138
	ds_read2_b32 v[32:33], v101 offset0:195 offset1:203
	ds_read2_b32 v[36:37], v12 offset0:4 offset1:12
	ds_read2_b32 v[40:41], v12 offset0:69 offset1:77
	ds_read2_b32 v[44:45], v12 offset0:134 offset1:142
	ds_read2_b32 v[48:49], v12 offset0:199 offset1:207
	s_waitcnt lgkmcnt(6)
	v_cvt_pk_bf16_f32 v60, v24, v20
	s_waitcnt lgkmcnt(4)
	v_cvt_pk_bf16_f32 v61, v28, v32
	s_waitcnt lgkmcnt(2)
	v_cvt_pk_bf16_f32 v62, v36, v40
	s_waitcnt lgkmcnt(0)
	v_cvt_pk_bf16_f32 v63, v44, v48
	v_add_u32_e32 v20, 8, v52
	global_store_dwordx4 v[56:57], v[60:63], off
	v_add_u32_e32 v56, 16, v52
	v_ashrrev_i32_e32 v57, 31, v56
	v_cvt_pk_bf16_f32 v60, v25, v21
	v_ashrrev_i32_e32 v21, 31, v20
	v_lshlrev_b64 v[20:21], 12, v[20:21]
	v_cvt_pk_bf16_f32 v61, v29, v33
	v_cvt_pk_bf16_f32 v62, v37, v41
	v_cvt_pk_bf16_f32 v63, v45, v49
	v_lshl_add_u64 v[20:21], v[16:17], 0, v[20:21]
	global_store_dwordx4 v[20:21], v[60:63], off
	ds_read2_b32 v[20:21], v101 offset0:81 offset1:89
	ds_read2_b32 v[24:25], v101 offset0:16 offset1:24
	ds_read2_b32 v[28:29], v101 offset0:146 offset1:154
	ds_read2_b32 v[32:33], v101 offset0:211 offset1:219
	ds_read2_b32 v[36:37], v12 offset0:20 offset1:28
	ds_read2_b32 v[40:41], v12 offset0:85 offset1:93
	ds_read2_b32 v[44:45], v12 offset0:150 offset1:158
	ds_read2_b32 v[48:49], v12 offset0:215 offset1:223
	v_lshlrev_b64 v[56:57], 12, v[56:57]
	s_waitcnt lgkmcnt(6)
	v_cvt_pk_bf16_f32 v60, v24, v20
	s_waitcnt lgkmcnt(4)
	v_cvt_pk_bf16_f32 v61, v28, v32
	s_waitcnt lgkmcnt(2)
	v_cvt_pk_bf16_f32 v62, v36, v40
	s_waitcnt lgkmcnt(0)
	v_cvt_pk_bf16_f32 v63, v44, v48
	v_lshl_add_u64 v[56:57], v[16:17], 0, v[56:57]
	v_add_u32_e32 v20, 24, v52
	global_store_dwordx4 v[56:57], v[60:63], off
	v_add_u32_e32 v56, 32, v52
	v_ashrrev_i32_e32 v57, 31, v56
	v_cvt_pk_bf16_f32 v60, v25, v21
	v_ashrrev_i32_e32 v21, 31, v20
	v_lshlrev_b64 v[20:21], 12, v[20:21]
	v_cvt_pk_bf16_f32 v61, v29, v33
	v_cvt_pk_bf16_f32 v62, v37, v41
	v_cvt_pk_bf16_f32 v63, v45, v49
	v_lshl_add_u64 v[20:21], v[16:17], 0, v[20:21]
	global_store_dwordx4 v[20:21], v[60:63], off
	ds_read2_b32 v[20:21], v101 offset0:32 offset1:40
	ds_read2_b32 v[24:25], v101 offset0:97 offset1:105
	ds_read2_b32 v[28:29], v101 offset0:162 offset1:170
	ds_read2_b32 v[32:33], v101 offset0:227 offset1:235
	ds_read2_b32 v[36:37], v12 offset0:36 offset1:44
	ds_read2_b32 v[40:41], v12 offset0:101 offset1:109
	ds_read2_b32 v[44:45], v12 offset0:166 offset1:174
	ds_read2_b32 v[48:49], v12 offset0:231 offset1:239
	v_lshlrev_b64 v[56:57], 12, v[56:57]
	s_waitcnt lgkmcnt(6)
	v_cvt_pk_bf16_f32 v60, v20, v24
	s_waitcnt lgkmcnt(4)
	v_cvt_pk_bf16_f32 v61, v28, v32
	s_waitcnt lgkmcnt(2)
	v_cvt_pk_bf16_f32 v62, v36, v40
	s_waitcnt lgkmcnt(0)
	v_cvt_pk_bf16_f32 v63, v44, v48
	v_lshl_add_u64 v[56:57], v[16:17], 0, v[56:57]
	v_add_u32_e32 v20, 40, v52
	global_store_dwordx4 v[56:57], v[60:63], off
	v_add_u32_e32 v56, 48, v52
	v_ashrrev_i32_e32 v57, 31, v56
	v_cvt_pk_bf16_f32 v60, v21, v25
	v_ashrrev_i32_e32 v21, 31, v20
	v_lshlrev_b64 v[20:21], 12, v[20:21]
	v_cvt_pk_bf16_f32 v61, v29, v33
	v_cvt_pk_bf16_f32 v62, v37, v41
	v_cvt_pk_bf16_f32 v63, v45, v49
	v_lshl_add_u64 v[20:21], v[16:17], 0, v[20:21]
	global_store_dwordx4 v[20:21], v[60:63], off
	ds_read2_b32 v[20:21], v101 offset0:48 offset1:56
	ds_read2_b32 v[24:25], v101 offset0:113 offset1:121
	ds_read2_b32 v[28:29], v101 offset0:178 offset1:186
	ds_read2_b32 v[32:33], v101 offset0:243 offset1:251
	ds_read2_b32 v[36:37], v12 offset0:52 offset1:60
	ds_read2_b32 v[40:41], v12 offset0:117 offset1:125
	ds_read2_b32 v[44:45], v12 offset0:182 offset1:190
	ds_read2_b32 v[48:49], v12 offset0:247 offset1:255
	v_lshlrev_b64 v[56:57], 12, v[56:57]
	s_waitcnt lgkmcnt(6)
	v_cvt_pk_bf16_f32 v60, v20, v24
	s_waitcnt lgkmcnt(4)
	v_cvt_pk_bf16_f32 v61, v28, v32
	s_waitcnt lgkmcnt(2)
	v_cvt_pk_bf16_f32 v62, v36, v40
	s_waitcnt lgkmcnt(0)
	v_cvt_pk_bf16_f32 v63, v44, v48
	v_lshl_add_u64 v[56:57], v[16:17], 0, v[56:57]
	v_add_u32_e32 v20, 56, v52
	global_store_dwordx4 v[56:57], v[60:63], off
	s_nop 1
	v_cvt_pk_bf16_f32 v60, v21, v25
	v_ashrrev_i32_e32 v21, 31, v20
	v_lshlrev_b64 v[20:21], 12, v[20:21]
	v_cvt_pk_bf16_f32 v61, v29, v33
	v_cvt_pk_bf16_f32 v62, v37, v41
	v_cvt_pk_bf16_f32 v63, v45, v49
	v_lshl_add_u64 v[16:17], v[16:17], 0, v[20:21]
	global_store_dwordx4 v[16:17], v[60:63], off
	s_waitcnt lgkmcnt(0)
	s_cbranch_scc1 .LBB0_454
